# QE also written fragment-contiguous from LDS and read contiguously by the scan; q cache lines touched ahead of the serialized per-token loads in gla_prep
# speedup vs baseline: 1.0627x; 1.0122x over previous
.LBB0_202:
	s_lshr_b32 s30, s23, 6
	s_lshl_b32 s30, s30, 19
	s_bfe_u32 s31, s23, 0x20004
	s_lshl_b32 s31, s31, 22
	s_or_b32 s30, s30, s31
	s_lshr_b32 s6, s23, 4
	v_lshlrev_b32_e32 v34, 14, v200
	s_and_b32 s6, s6, 3
	v_lshl_or_b32 v34, s3, 23, v34
	s_lshl_b32 s3, s23, 5
	s_lshl_b32 s66, s6, 9
	s_and_b32 s24, s3, 0x1e0
	s_or_b32 s3, s24, s66
	s_lshl_b32 s18, s2, 4
	s_lshl_b32 s2, s2, 10
	v_or_b32_e32 v42, s3, v200
	s_ashr_i32 s19, s18, 31
	s_ashr_i32 s3, s2, 31
	s_lshl_b32 s25, s6, 10
	s_lshl_b32 s28, s5, 6
	v_add_u32_e32 v32, s4, v201
	s_lshl_b32 s4, s6, 13
	v_lshl_or_b32 v34, s5, 19, v34
	v_lshl_add_u32 v36, s6, 8, v201
	s_mov_b32 s5, s67
	s_lshl_b64 s[16:17], s[18:19], 17
	s_lshl_b64 s[6:7], s[18:19], 15
	s_lshl_b64 s[8:9], s[2:3], 1
	s_lshl_b64 s[2:3], s[18:19], 18
	s_lshl_b64 s[18:19], s[18:19], 12
	v_lshl_add_u64 v[40:41], v[158:159], 0, s[4:5]
	s_add_u32 s5, s20, s18
	v_lshl_add_u64 v[38:39], v[156:157], 0, s[66:67]
	s_addc_u32 s27, s21, s19
	v_lshl_add_u64 v[38:39], v[38:39], 0, s[16:17]
	s_add_u32 s26, s5, s25
	s_mov_b32 s5, 0x10000
	v_ashrrev_i32_e32 v37, 31, v36
	v_lshl_add_u64 v[40:41], v[40:41], 0, s[6:7]
	v_lshrrev_b32_e32 v214, 6, v152
	v_and_b32_e32 v215, 63, v152
	v_lshlrev_b32_e32 v214, 13, v214
	v_lshl_or_b32 v214, v215, 4, v214
	v_add_u32_e32 v194, s30, v214
	v_mov_b32_e32 v195, 0
	v_lshl_add_u64 v[38:39], s[0:1], 0, v[194:195]
	v_add_co_u32_e32 v38, vcc, 0xe801000, v38
	s_nop 1
	v_addc_co_u32_e32 v39, vcc, 0, v39, vcc
	global_load_dwordx4 v[96:99], v[38:39], off offset:-4096
	global_load_dwordx4 v[88:91], v[38:39], off offset:-3072
	global_load_dwordx4 v[80:83], v[38:39], off offset:-2048
	global_load_dwordx4 v[72:75], v[38:39], off offset:-1024
	global_load_dwordx4 v[64:67], v[40:41], off
	v_lshlrev_b64 v[36:37], 14, v[36:37]
	v_lshlrev_b32_e32 v42, 14, v42
	v_mov_b32_e32 v43, v187
	v_lshl_add_u64 v[36:37], v[162:163], 0, v[36:37]
	global_load_dwordx4 v[100:103], v[38:39], off
	global_load_dwordx4 v[92:95], v[38:39], off offset:1024
	global_load_dwordx4 v[84:87], v[38:39], off offset:2048
	global_load_dwordx4 v[76:79], v[38:39], off offset:3072
	v_add_co_u32_e32 v38, vcc, s29, v40
	v_lshl_add_u64 v[42:43], v[160:161], 0, v[42:43]
	s_nop 0
	v_addc_co_u32_e32 v39, vcc, 0, v41, vcc
	v_lshl_add_u64 v[36:37], v[36:37], 0, s[8:9]
	v_lshl_add_u64 v[42:43], v[42:43], 0, s[8:9]
	global_load_dwordx4 v[68:71], v[38:39], off
	global_load_dwordx4 v[108:111], v[42:43], off
	global_load_dwordx4 v[104:107], v[42:43], off offset:32
	global_load_dwordx4 v[112:115], v[42:43], off offset:64
	global_load_dwordx4 v[116:119], v[42:43], off offset:96
	v_lshrrev_b32_e32 v214, 6, v152
	v_and_b32_e32 v215, 63, v152
	v_lshlrev_b32_e32 v214, 13, v214
	v_lshl_or_b32 v214, v215, 4, v214
	v_add_u32_e32 v194, s30, v214
	v_mov_b32_e32 v195, 0
	v_lshl_add_u64 v[36:37], s[0:1], 0, v[194:195]
	v_add_co_u32_e32 v36, vcc, 0xd001000, v36
	s_nop 1
	v_addc_co_u32_e32 v37, vcc, 0, v37, vcc
	global_load_dwordx4 v[148:151], v[36:37], off offset:-4096
	global_load_dwordx4 v[144:147], v[36:37], off offset:-3072
	global_load_dwordx4 v[140:143], v[36:37], off offset:-2048
	global_load_dwordx4 v[136:139], v[36:37], off offset:-1024
	s_addc_u32 s27, s27, 0
	s_nop 0
	global_load_dwordx4 v[132:135], v[36:37], off
	global_load_dwordx4 v[128:131], v[36:37], off offset:1024
	global_load_dwordx4 v[124:127], v[36:37], off offset:2048
	global_load_dwordx4 v[120:123], v[36:37], off offset:3072
	v_lshl_add_u64 v[36:37], v[152:153], 2, s[26:27]
	s_barrier
	global_load_dword v36, v[36:37], off
	v_ashrrev_i32_e32 v33, 31, v32
	v_lshlrev_b64 v[32:33], 14, v[32:33]
	s_or_b32 s18, s18, s25
	v_mov_b32_e32 v35, v187
	v_lshl_add_u64 v[180:181], s[18:19], 0, v[170:171]
	s_or_b32 s18, s28, s25
	v_or_b32_e32 v32, v154, v32
	s_or_b32 s18, s2, s18
	s_mov_b32 s19, s3
	s_or_b32 s16, s16, s66
	s_or_b32 s6, s6, s4
	v_lshl_add_u64 v[32:33], v[178:179], 0, v[34:35]
	s_mov_b32 s5, 0
	v_lshl_add_u64 v[182:183], s[18:19], 0, v[172:173]
	v_lshl_add_u64 v[192:193], s[16:17], 0, v[174:175]
	v_lshl_add_u64 v[196:197], s[6:7], 0, v[176:177]
	v_lshl_add_u64 v[198:199], v[32:33], 0, s[8:9]
	s_waitcnt vmcnt(0)
	ds_write_b32 v155, v36 offset:32768
	s_waitcnt lgkmcnt(0)
	s_barrier
.LBB0_203:
	v_lshl_add_u64 v[32:33], s[0:1], 0, v[180:181]
	global_load_dword v205, v[32:33], off
	v_cvt_pk_bf16_f32 v32, v16, v17
	v_cvt_pk_bf16_f32 v33, v18, v19
	v_cvt_pk_bf16_f32 v34, v20, v21
	v_cvt_pk_bf16_f32 v35, v22, v23
	s_mov_b32 s4, 0xc020000
	s_waitcnt vmcnt(10)
	v_cndmask_b32_e64 v206, v119, v115, s[14:15]
	v_mfma_f32_32x32x16_bf16 v[48:63], v[96:99], v[32:35], 0
	v_cvt_pk_bf16_f32 v96, v24, v25
	v_cvt_pk_bf16_f32 v97, v26, v27
	v_cvt_pk_bf16_f32 v98, v28, v29
	v_cvt_pk_bf16_f32 v99, v30, v31
	v_cndmask_b32_e64 v207, v118, v114, s[14:15]
	v_cndmask_b32_e64 v208, v117, v113, s[14:15]
	v_cndmask_b32_e64 v209, v116, v112, s[14:15]
	v_mfma_f32_32x32x16_bf16 v[48:63], v[88:91], v[96:99], v[48:63]
	v_cvt_pk_bf16_f32 v88, v0, v1
	v_cvt_pk_bf16_f32 v89, v2, v3
	v_cvt_pk_bf16_f32 v90, v4, v5
	v_cvt_pk_bf16_f32 v91, v6, v7
	v_cndmask_b32_e64 v210, v209, v104, s[12:13]
	v_cndmask_b32_e64 v211, v208, v105, s[12:13]
	v_cndmask_b32_e64 v207, v207, v106, s[12:13]
	v_mfma_f32_32x32x16_bf16 v[32:47], v[100:103], v[32:35], 0
	v_cndmask_b32_e64 v206, v206, v107, s[12:13]
	v_cndmask_b32_e64 v209, v206, v111, s[10:11]
	v_cndmask_b32_e64 v208, v207, v110, s[10:11]
	v_cndmask_b32_e64 v207, v211, v109, s[10:11]
	v_cndmask_b32_e64 v206, v210, v108, s[10:11]
	v_add_u32_e32 v210, 0x1800, v204
	v_add_u32_e32 v211, 0x1c00, v204
	v_mfma_f32_32x32x16_bf16 v[48:63], v[80:83], v[88:91], v[48:63]
	v_cvt_pk_bf16_f32 v80, v8, v9
	v_cvt_pk_bf16_f32 v81, v10, v11
	v_cvt_pk_bf16_f32 v82, v12, v13
	v_cvt_pk_bf16_f32 v83, v14, v15
	s_mov_b64 s[6:7], 0x8000
	v_lshl_add_u64 v[180:181], v[180:181], 0, s[86:87]
	s_waitcnt vmcnt(2)
	v_mfma_f32_32x32x16_bf16 v[16:31], v[148:151], v[108:111], v[16:31]
	v_mfma_f32_32x32x16_bf16 v[0:15], v[132:135], v[108:111], v[0:15]
	v_mfma_f32_32x32x16_bf16 v[32:47], v[92:95], v[96:99], v[32:47]
	v_mfma_f32_32x32x16_bf16 v[16:31], v[144:147], v[104:107], v[16:31]
	v_mfma_f32_32x32x16_bf16 v[0:15], v[128:131], v[104:107], v[0:15]
	v_mfma_f32_32x32x16_bf16 v[32:47], v[84:87], v[88:91], v[32:47]
	v_mfma_f32_32x32x16_bf16 v[48:63], v[72:75], v[80:83], v[48:63]
	v_mfma_f32_32x32x16_bf16 v[16:31], v[140:143], v[112:115], v[16:31]
	v_mfma_f32_32x32x16_bf16 v[0:15], v[124:127], v[112:115], v[0:15]
	v_mfma_f32_32x32x16_bf16 v[32:47], v[76:79], v[80:83], v[32:47]
	v_lshl_add_u64 v[76:77], s[0:1], 0, v[194:195]
	v_add_co_u32_e32 v216, vcc, 0xe809000, v76
	s_mov_b32 s4, 0xc030000
	s_nop 0
	v_addc_co_u32_e32 v217, vcc, 0, v77, vcc
	v_mfma_f32_32x32x16_bf16 v[48:63], v[64:67], v[206:209], v[48:63]
	v_lshl_add_u64 v[64:65], s[0:1], 0, v[196:197]
	s_mov_b32 s4, 0xe009000
	global_load_dwordx4 v[96:99], v[216:217], off offset:-4096
	global_load_dwordx4 v[88:91], v[216:217], off offset:-3072
	global_load_dwordx4 v[80:83], v[216:217], off offset:-2048
	global_load_dwordx4 v[72:75], v[216:217], off offset:-1024
	global_load_dwordx4 v[100:103], v[216:217], off
	global_load_dwordx4 v[92:95], v[216:217], off offset:1024
	global_load_dwordx4 v[84:87], v[216:217], off offset:2048
	global_load_dwordx4 v[76:79], v[216:217], off offset:3072
	v_lshl_add_u64 v[192:193], v[192:193], 0, s[58:59]
	v_mfma_f32_32x32x16_bf16 v[16:31], v[136:139], v[116:119], v[16:31]
	v_lshl_add_u64 v[196:197], v[196:197], 0, s[6:7]
	v_mfma_f32_32x32x16_bf16 v[0:15], v[120:123], v[116:119], v[0:15]
	v_lshl_add_u64 v[116:117], s[0:1], 0, v[198:199]
	v_lshl_add_u64 v[198:199], v[198:199], 0, s[94:95]
	v_mfma_f32_32x32x16_bf16 v[32:47], v[68:71], v[206:209], v[32:47]
	v_add_co_u32_e32 v68, vcc, s4, v64
	s_and_b32 s4, s5, 0x100
	s_nop 0
	v_addc_co_u32_e32 v69, vcc, 0, v65, vcc
	v_lshl_add_u32 v206, s4, 2, v202
	global_load_dwordx4 v[64:67], v[68:69], off offset:-4096
	s_nop 0
	global_load_dwordx4 v[68:71], v[68:69], off
	ds_read_b128 v[136:139], v206 offset:32768
	ds_read_b128 v[140:143], v206 offset:32800
	ds_read_b128 v[104:107], v206 offset:32896
	s_mov_b32 s4, 0xd080000
	s_addk_i32 s5, 0x100
	s_waitcnt lgkmcnt(2)
	v_pk_mul_f32 v[16:17], v[16:17], v[136:137]
	v_pk_mul_f32 v[18:19], v[18:19], v[138:139]
	ds_read_b128 v[136:139], v206 offset:32832
	s_waitcnt lgkmcnt(1)
	v_pk_mul_f32 v[0:1], v[0:1], v[104:105]
	v_pk_mul_f32 v[2:3], v[2:3], v[106:107]
	ds_read_b128 v[104:107], v206 offset:32928
	v_pk_mul_f32 v[20:21], v[20:21], v[140:141]
	s_waitcnt lgkmcnt(1)
	v_pk_mul_f32 v[24:25], v[24:25], v[136:137]
	v_pk_mul_f32 v[26:27], v[26:27], v[138:139]
	ds_read_b128 v[136:139], v206 offset:32864
	s_waitcnt lgkmcnt(1)
	v_pk_mul_f32 v[4:5], v[4:5], v[104:105]
	v_pk_mul_f32 v[6:7], v[6:7], v[106:107]
	ds_read_b128 v[104:107], v206 offset:32960
	v_pk_mul_f32 v[22:23], v[22:23], v[142:143]
	s_waitcnt lgkmcnt(1)
	v_pk_mul_f32 v[28:29], v[28:29], v[136:137]
	v_lshl_add_u64 v[136:137], s[0:1], 0, v[194:195]
	v_add_co_u32_e32 v212, vcc, 0xd009000, v136
	s_waitcnt lgkmcnt(0)
	v_pk_mul_f32 v[8:9], v[8:9], v[104:105]
	v_pk_mul_f32 v[10:11], v[10:11], v[106:107]
	ds_read_b128 v[104:107], v206 offset:32992
	v_addc_co_u32_e32 v213, vcc, 0, v137, vcc
	v_pk_mul_f32 v[30:31], v[30:31], v[138:139]
	s_nop 0
	s_waitcnt lgkmcnt(0)
	v_pk_mul_f32 v[12:13], v[12:13], v[104:105]
	v_pk_mul_f32 v[14:15], v[14:15], v[106:107]
	global_load_dwordx4 v[108:111], v[116:117], off offset:-64
	global_load_dwordx4 v[104:107], v[116:117], off offset:-32
	global_load_dwordx4 v[112:115], v[116:117], off
	s_nop 0
	global_load_dwordx4 v[116:119], v[116:117], off offset:32
	s_nop 0
	global_load_dwordx4 v[120:123], v[212:213], off offset:3072
	global_load_dwordx4 v[124:127], v[212:213], off offset:2048
	global_load_dwordx4 v[128:131], v[212:213], off offset:1024
	global_load_dwordx4 v[132:135], v[212:213], off
	global_load_dwordx4 v[136:139], v[212:213], off offset:-1024
	global_load_dwordx4 v[140:143], v[212:213], off offset:-2048
	global_load_dwordx4 v[144:147], v[212:213], off offset:-3072
	global_load_dwordx4 v[148:151], v[212:213], off offset:-4096
	s_and_b32 s4, s5, 0x100
	v_lshl_add_u32 v206, s4, 2, v155
	s_waitcnt vmcnt(22)
	ds_write_b32 v206, v205 offset:32768
	ds_write2_b32 v204, v48, v49 offset1:32
	ds_write2_b32 v204, v50, v51 offset0:64 offset1:96
	v_add_u32_e32 v205, 0x400, v204
	v_add_u32_e32 v206, 0x800, v204
	v_add_u32_e32 v207, 0xc00, v204
	v_add_u32_e32 v208, 0x1000, v204
	v_add_u32_e32 v209, 0x1400, v204
	ds_write2_b32 v205, v52, v53 offset1:32
	ds_write2_b32 v205, v54, v55 offset0:64 offset1:96
	ds_write2_b32 v206, v56, v57 offset1:32
	ds_write2_b32 v206, v58, v59 offset0:64 offset1:96
	ds_write2_b32 v207, v60, v61 offset1:32
	ds_write2_b32 v207, v62, v63 offset0:64 offset1:96
	ds_write2_b32 v208, v32, v33 offset1:32
	ds_write2_b32 v208, v34, v35 offset0:64 offset1:96
	ds_write2_b32 v209, v36, v37 offset1:32
	ds_write2_b32 v209, v38, v39 offset0:64 offset1:96
	ds_write2_b32 v210, v40, v41 offset1:32
	ds_write2_b32 v210, v42, v43 offset0:64 offset1:96
	ds_write2_b32 v211, v44, v45 offset1:32
	ds_write2_b32 v211, v46, v47 offset0:64 offset1:96
	s_waitcnt lgkmcnt(0)
	s_barrier
	ds_read_b128 v[32:35], v203
	ds_read_b128 v[36:39], v203 offset:16
	ds_read_b128 v[40:43], v203 offset:8192
	ds_read_b128 v[44:47], v203 offset:16384
	ds_read_b128 v[48:51], v203 offset:24576
	v_lshl_add_u64 v[194:195], v[194:195], 0, s[6:7]
	s_cmpk_eq_i32 s5, 0xf00
	s_waitcnt lgkmcnt(2)
	v_pk_add_f32 v[32:33], v[32:33], v[40:41]
	s_waitcnt lgkmcnt(1)
	v_pk_add_f32 v[32:33], v[32:33], v[44:45]
	s_waitcnt lgkmcnt(0)
	v_pk_add_f32 v[48:49], v[32:33], v[48:49]
	v_pk_add_f32 v[32:33], v[34:35], v[42:43]
	ds_read_b128 v[40:43], v203 offset:16400
	v_pk_add_f32 v[32:33], v[32:33], v[46:47]
	ds_read_b128 v[44:47], v203 offset:24592
	v_pk_add_f32 v[50:51], v[32:33], v[50:51]
	ds_read_b128 v[32:35], v203 offset:8208
	s_waitcnt lgkmcnt(0)
	v_pk_add_f32 v[32:33], v[36:37], v[32:33]
	s_nop 0
	v_pk_add_f32 v[32:33], v[32:33], v[40:41]
	s_nop 0
	v_pk_add_f32 v[36:37], v[32:33], v[44:45]
	v_pk_add_f32 v[32:33], v[38:39], v[34:35]
	v_cvt_pk_bf16_f32 v34, v36, v37
	v_pk_add_f32 v[32:33], v[32:33], v[42:43]
	v_lshl_add_u64 v[36:37], s[0:1], 0, v[182:183]
	v_pk_add_f32 v[38:39], v[32:33], v[46:47]
	v_cvt_pk_bf16_f32 v32, v48, v49
	v_cvt_pk_bf16_f32 v33, v50, v51
	v_cvt_pk_bf16_f32 v35, v38, v39
	v_lshl_add_u64 v[182:183], v[182:183], 0, s[90:91]
	global_store_dwordx4 v[36:37], v[32:35], off offset:-8
	s_barrier
	s_cbranch_scc0 .LBB0_203
	v_cvt_pk_bf16_f32 v16, v16, v17
	v_cvt_pk_bf16_f32 v17, v18, v19
	v_cvt_pk_bf16_f32 v18, v20, v21
	v_cvt_pk_bf16_f32 v19, v22, v23
	v_cvt_pk_bf16_f32 v0, v0, v1
	v_cvt_pk_bf16_f32 v1, v2, v3
	s_waitcnt vmcnt(22)
	v_mfma_f32_32x32x16_bf16 v[48:63], v[96:99], v[16:19], 0
	v_cvt_pk_bf16_f32 v2, v4, v5
	v_cvt_pk_bf16_f32 v3, v6, v7
	v_cvt_pk_bf16_f32 v4, v8, v9
	v_cvt_pk_bf16_f32 v5, v10, v11
	v_cvt_pk_bf16_f32 v6, v12, v13
	v_cvt_pk_bf16_f32 v7, v14, v15
	s_lshl_b32 s66, s66, 1
	s_waitcnt vmcnt(18)
	v_mfma_f32_32x32x16_bf16 v[32:47], v[100:103], v[16:19], 0
	v_cvt_pk_bf16_f32 v16, v24, v25
	v_cvt_pk_bf16_f32 v17, v26, v27
	v_cvt_pk_bf16_f32 v18, v28, v29
	v_cvt_pk_bf16_f32 v19, v30, v31
	s_add_i32 s23, s23, s64
	s_add_i32 s22, s22, s64
	v_mfma_f32_32x32x16_bf16 v[48:63], v[88:91], v[16:19], v[48:63]
	s_waitcnt vmcnt(17)
	v_mfma_f32_32x32x16_bf16 v[32:47], v[92:95], v[16:19], v[32:47]
	v_mfma_f32_32x32x16_bf16 v[48:63], v[80:83], v[0:3], v[48:63]
	s_waitcnt vmcnt(16)
	v_mfma_f32_32x32x16_bf16 v[32:47], v[84:87], v[0:3], v[32:47]
	s_waitcnt vmcnt(9)
	v_cndmask_b32_e64 v0, v119, v115, s[14:15]
	v_cndmask_b32_e64 v1, v118, v114, s[14:15]
	v_cndmask_b32_e64 v2, v117, v113, s[14:15]
	v_cndmask_b32_e64 v3, v116, v112, s[14:15]
	v_cndmask_b32_e64 v8, v3, v104, s[12:13]
	v_cndmask_b32_e64 v9, v2, v105, s[12:13]
	v_cndmask_b32_e64 v1, v1, v106, s[12:13]
	v_mfma_f32_32x32x16_bf16 v[48:63], v[72:75], v[4:7], v[48:63]
	v_cndmask_b32_e64 v0, v0, v107, s[12:13]
	v_cndmask_b32_e64 v3, v0, v111, s[10:11]
	v_cndmask_b32_e64 v2, v1, v110, s[10:11]
	v_cndmask_b32_e64 v1, v9, v109, s[10:11]
	v_cndmask_b32_e64 v0, v8, v108, s[10:11]
	v_lshl_add_u64 v[8:9], v[164:165], 0, s[66:67]
	s_lshl_b32 s66, s24, 1
	v_mfma_f32_32x32x16_bf16 v[32:47], v[76:79], v[4:7], v[32:47]
	v_lshl_add_u64 v[8:9], v[8:9], 0, s[66:67]
	v_lshl_add_u64 v[8:9], v[8:9], 0, v[186:187]
	s_cmpk_gt_i32 s23, 0x1ff
	v_mfma_f32_32x32x16_bf16 v[48:63], v[64:67], v[0:3], v[48:63]
	v_lshl_add_u64 v[64:65], v[8:9], 0, s[2:3]
	ds_write_b32 v155, v187 offset:32768
	s_nop 9
	ds_write2_b32 v204, v48, v49 offset1:32
	v_mfma_f32_32x32x16_bf16 v[32:47], v[68:71], v[0:3], v[32:47]
	ds_write2_b32 v204, v50, v51 offset0:64 offset1:96
	ds_write2_b32 v205, v52, v53 offset1:32
	ds_write2_b32 v205, v54, v55 offset0:64 offset1:96
	ds_write2_b32 v206, v56, v57 offset1:32
	ds_write2_b32 v206, v58, v59 offset0:64 offset1:96
	ds_write2_b32 v207, v60, v61 offset1:32
	ds_write2_b32 v207, v62, v63 offset0:64 offset1:96
	s_nop 4
	ds_write2_b32 v208, v32, v33 offset1:32
	ds_write2_b32 v208, v34, v35 offset0:64 offset1:96
	ds_write2_b32 v209, v36, v37 offset1:32
	ds_write2_b32 v209, v38, v39 offset0:64 offset1:96
	ds_write2_b32 v210, v40, v41 offset1:32
	ds_write2_b32 v210, v42, v43 offset0:64 offset1:96
	ds_write2_b32 v211, v44, v45 offset1:32
	ds_write2_b32 v211, v46, v47 offset0:64 offset1:96
	s_waitcnt lgkmcnt(0)
	s_barrier
	ds_read_b128 v[0:3], v203 offset:8192
	ds_read_b128 v[4:7], v203
	ds_read_b128 v[8:11], v203 offset:16
	ds_read_b128 v[12:15], v203 offset:16384
	ds_read_b128 v[16:19], v203 offset:24576
	ds_read_b128 v[20:23], v203 offset:8208
	ds_read_b128 v[24:27], v203 offset:16400
	ds_read_b128 v[28:31], v203 offset:24592
	s_waitcnt lgkmcnt(6)
	v_pk_add_f32 v[0:1], v[4:5], v[0:1]
	v_pk_add_f32 v[2:3], v[6:7], v[2:3]
	s_waitcnt lgkmcnt(2)
	v_pk_add_f32 v[4:5], v[8:9], v[20:21]
	v_pk_add_f32 v[0:1], v[0:1], v[12:13]
	v_pk_add_f32 v[2:3], v[2:3], v[14:15]
	s_waitcnt lgkmcnt(1)
	v_pk_add_f32 v[4:5], v[4:5], v[24:25]
	v_pk_add_f32 v[6:7], v[10:11], v[22:23]
	v_pk_add_f32 v[0:1], v[0:1], v[16:17]
	v_pk_add_f32 v[2:3], v[2:3], v[18:19]
	s_waitcnt lgkmcnt(0)
	v_pk_add_f32 v[4:5], v[4:5], v[28:29]
	v_pk_add_f32 v[6:7], v[6:7], v[26:27]
	v_cvt_pk_bf16_f32 v0, v0, v1
	v_pk_add_f32 v[6:7], v[6:7], v[30:31]
	v_cvt_pk_bf16_f32 v1, v2, v3
	v_cvt_pk_bf16_f32 v2, v4, v5
	v_add_co_u32_e32 v4, vcc, 0x3c0000, v64
	v_cvt_pk_bf16_f32 v3, v6, v7
	s_nop 0
	v_addc_co_u32_e32 v5, vcc, 0, v65, vcc
	global_store_dwordx4 v[4:5], v[0:3], off
	s_barrier
	s_cbranch_scc0 .LBB0_198

.LBB0_224:
	s_lshl_b32 s0, s3, 4
	s_or_b32 s0, s0, s72
	s_lshl_b32 s0, s0, 12
	s_mov_b32 s1, 0
	v_lshl_add_u64 v[218:219], v[12:13], 0, s[0:1]
	global_load_ushort v220, v[218:219], off
	v_lshl_add_u64 v[218:219], v[218:219], 0, s[86:87]
	global_load_ushort v220, v[218:219], off
	v_lshl_add_u64 v[218:219], v[218:219], 0, s[86:87]
	global_load_ushort v220, v[218:219], off
	v_lshl_add_u64 v[218:219], v[218:219], 0, s[86:87]
	global_load_ushort v220, v[218:219], off
	v_lshl_add_u64 v[218:219], v[218:219], 0, s[86:87]
	global_load_ushort v220, v[218:219], off
	v_lshl_add_u64 v[218:219], v[218:219], 0, s[86:87]
	global_load_ushort v220, v[218:219], off
	v_lshl_add_u64 v[218:219], v[218:219], 0, s[86:87]
	global_load_ushort v220, v[218:219], off
	v_lshl_add_u64 v[218:219], v[218:219], 0, s[86:87]
	global_load_ushort v220, v[218:219], off
	v_lshl_add_u64 v[218:219], v[218:219], 0, s[86:87]
	global_load_ushort v220, v[218:219], off
	v_lshl_add_u64 v[218:219], v[218:219], 0, s[86:87]
	global_load_ushort v220, v[218:219], off
	v_lshl_add_u64 v[218:219], v[218:219], 0, s[86:87]
	global_load_ushort v220, v[218:219], off
	v_lshl_add_u64 v[218:219], v[218:219], 0, s[86:87]
	global_load_ushort v220, v[218:219], off
	v_lshl_add_u64 v[218:219], v[218:219], 0, s[86:87]
	global_load_ushort v220, v[218:219], off
	v_lshl_add_u64 v[218:219], v[218:219], 0, s[86:87]
	global_load_ushort v220, v[218:219], off
	v_lshl_add_u64 v[218:219], v[218:219], 0, s[86:87]
	global_load_ushort v220, v[218:219], off
	v_lshl_add_u64 v[218:219], v[218:219], 0, s[86:87]
	global_load_ushort v220, v[218:219], off
	s_lshl_b32 s0, s3, 10
	s_add_i32 s0, s0, 0x10000
	v_mov_b32_e32 v14, s0
	ds_read_b128 v[60:63], v14
	ds_read_b128 v[64:67], v14 offset:16
	ds_read_b128 v[68:71], v14 offset:32
	ds_read_b128 v[72:75], v14 offset:48
	s_lshl_b32 s20, s3, 4
	s_waitcnt vmcnt(0) lgkmcnt(3)
	v_fma_f32 v56, v133, v60, v134
	v_fmac_f32_e32 v56, v126, v61
	v_fmac_f32_e32 v56, v127, v62
	v_fmac_f32_e32 v56, v128, v63
	s_waitcnt lgkmcnt(2)
	v_fmac_f32_e32 v56, v129, v64
	v_fmac_f32_e32 v56, v130, v65
	v_fmac_f32_e32 v56, v131, v66
	v_fmac_f32_e32 v56, v132, v67
	s_waitcnt lgkmcnt(1)
	v_fmac_f32_e32 v56, v0, v68
	v_fmac_f32_e32 v56, v1, v69
	v_pk_mul_f32 v[14:15], v[2:3], v[70:71]
	s_or_b32 s50, s20, s72
	v_add_f32_e32 v14, v56, v14
	v_add_f32_e32 v56, v14, v15
	s_waitcnt lgkmcnt(0)
	v_pk_mul_f32 v[14:15], v[4:5], v[72:73]
	s_ashr_i32 s51, s50, 31
	v_add_f32_e32 v14, v56, v14
	v_add_f32_e32 v56, v14, v15
	v_pk_mul_f32 v[14:15], v[6:7], v[74:75]
	s_lshl_b64 s[0:1], s[50:51], 12
	v_add_f32_e32 v14, v56, v14
	v_add_f32_e32 v14, v14, v15
	v_min_f32_e32 v15, 0, v14
	v_mul_f32_e64 v14, |v14|, s65
	v_exp_f32_e32 v14, v14
	s_or_b32 s66, s20, 1
	s_or_b32 s74, s66, s72
	s_ashr_i32 s75, s74, 31
	v_add_f32_e32 v14, 1.0, v14
	v_cmp_gt_f32_e64 s[42:43], s80, v14
	s_or_b32 s73, s20, 2
	s_or_b32 s76, s73, s72
	v_cndmask_b32_e64 v56, 0, 32, s[42:43]
	v_ldexp_f32 v14, v14, v56
	v_log_f32_e32 v14, v14
	s_ashr_i32 s77, s76, 31
	s_or_b32 s68, s20, 3
	s_or_b32 s82, s68, s72
	v_mul_f32_e32 v56, 0x3f317217, v14
	v_fma_f32 v56, v14, s81, -v56
	v_fmac_f32_e32 v56, 0x3377d1cf, v14
	v_fmac_f32_e32 v56, 0x3f317217, v14
	v_cmp_lt_f32_e64 s[44:45], |v14|, s71
	s_ashr_i32 s83, s82, 31
	s_or_b32 s69, s20, 4
	v_cndmask_b32_e64 v14, v14, v56, s[44:45]
	v_cndmask_b32_e64 v56, 0, v236, s[42:43]
	v_sub_f32_e32 v14, v14, v56
	v_sub_f32_e32 v14, v15, v14
	v_fmac_f32_e32 v58, 0x3d800000, v14
	v_lshl_add_u64 v[14:15], v[12:13], 0, s[0:1]
	global_load_ushort v56, v[14:15], off
	s_lshl_b32 s0, s66, 6
	s_add_i32 s0, s0, 0x10000
	s_or_b32 s96, s69, s72
	s_ashr_i32 s97, s96, 31
	s_or_b32 s10, s20, 5
	s_or_b32 s8, s10, s72
	s_ashr_i32 s9, s8, 31
	s_or_b32 s11, s20, 6
	s_or_b32 s46, s11, s72
	s_ashr_i32 s47, s46, 31
	s_or_b32 s12, s20, 7
	s_or_b32 s60, s12, s72
	s_ashr_i32 s61, s60, 31
	s_or_b32 s13, s20, 8
	s_or_b32 s62, s13, s72
	s_ashr_i32 s63, s62, 31
	s_or_b32 s14, s20, 9
	s_or_b32 s56, s14, s72
	s_ashr_i32 s57, s56, 31
	s_or_b32 s15, s20, 10
	s_or_b32 s16, s20, 11
	s_or_b32 s6, s16, s72
	s_ashr_i32 s7, s6, 31
	s_or_b32 s17, s20, 12
	s_or_b32 s54, s17, s72
	s_ashr_i32 s55, s54, 31
	s_or_b32 s18, s20, 13
	s_or_b32 s48, s18, s72
	s_ashr_i32 s49, s48, 31
	s_or_b32 s19, s20, 14
	s_or_b32 s20, s20, 15
	s_lshl_b32 s21, s20, 6
	s_add_i32 s21, s21, 0x10000
	v_mul_f32_e32 v161, 0x3fb8aa3b, v58
	v_exp_f32_e32 v161, v161
	v_lshl_add_u32 v179, s73, 9, v112
	v_lshl_add_u32 v181, s68, 9, v113
	v_lshl_add_u32 v192, s12, 9, v117
	s_waitcnt vmcnt(0)
	v_lshlrev_b32_e32 v160, 16, v56
	v_mov_b32_e32 v56, s0
	ds_read_b128 v[60:63], v56
	ds_read_b128 v[64:67], v56 offset:16
	ds_read_b128 v[68:71], v56 offset:32
	ds_read_b128 v[72:75], v56 offset:48
	s_lshl_b64 s[0:1], s[74:75], 12
	s_waitcnt lgkmcnt(3)
	v_fma_f32 v59, v133, v60, v134
	v_fmac_f32_e32 v59, v126, v61
	v_fmac_f32_e32 v59, v127, v62
	v_fmac_f32_e32 v59, v128, v63
	s_waitcnt lgkmcnt(2)
	v_fmac_f32_e32 v59, v129, v64
	v_fmac_f32_e32 v59, v130, v65
	v_fmac_f32_e32 v59, v131, v66
	v_fmac_f32_e32 v59, v132, v67
	s_waitcnt lgkmcnt(1)
	v_fmac_f32_e32 v59, v0, v68
	v_fmac_f32_e32 v59, v1, v69
	v_pk_mul_f32 v[56:57], v[2:3], v[70:71]
	v_mul_f32_e32 v160, 0x3d800000, v160
	v_add_f32_e32 v56, v59, v56
	v_add_f32_e32 v59, v56, v57
	s_waitcnt lgkmcnt(0)
	v_pk_mul_f32 v[56:57], v[4:5], v[72:73]
	v_mul_f32_e32 v160, v160, v161
	v_add_f32_e32 v56, v59, v56
	v_add_f32_e32 v59, v56, v57
	v_pk_mul_f32 v[56:57], v[6:7], v[74:75]
	s_nop 0
	v_add_f32_e32 v56, v59, v56
	v_add_f32_e32 v56, v56, v57
	v_min_f32_e32 v57, 0, v56
	v_mul_f32_e64 v56, |v56|, s65
	v_exp_f32_e32 v56, v56
	s_nop 0
	v_add_f32_e32 v56, 1.0, v56
	v_cmp_gt_f32_e64 s[42:43], s80, v56
	s_nop 1
	v_cndmask_b32_e64 v59, 0, 32, s[42:43]
	v_ldexp_f32 v56, v56, v59
	v_log_f32_e32 v56, v56
	s_nop 0
	v_mul_f32_e32 v59, 0x3f317217, v56
	v_fma_f32 v59, v56, s81, -v59
	v_fmac_f32_e32 v59, 0x3377d1cf, v56
	v_fmac_f32_e32 v59, 0x3f317217, v56
	v_cmp_lt_f32_e64 s[44:45], |v56|, s71
	s_nop 1
	v_cndmask_b32_e64 v56, v56, v59, s[44:45]
	v_cndmask_b32_e64 v59, 0, v236, s[42:43]
	v_sub_f32_e32 v56, v56, v59
	v_sub_f32_e32 v56, v57, v56
	v_fmamk_f32 v59, v56, 0x3d800000, v58
	v_lshl_add_u64 v[56:57], v[12:13], 0, s[0:1]
	global_load_ushort v60, v[56:57], off
	s_lshl_b32 s0, s73, 6
	s_add_i32 s0, s0, 0x10000
	v_mov_b32_e32 v72, s0
	s_lshl_b64 s[0:1], s[76:77], 12
	v_mul_f32_e32 v58, 0xbfb8aa3b, v58
	v_exp_f32_e32 v58, v58
	s_waitcnt vmcnt(0)
	v_lshlrev_b32_e32 v88, 16, v60
	ds_read_b128 v[60:63], v72
	ds_read_b128 v[64:67], v72 offset:16
	ds_read_b128 v[68:71], v72 offset:32
	ds_read_b128 v[72:75], v72 offset:48
	s_waitcnt lgkmcnt(3)
	v_fma_f32 v76, v133, v60, v134
	v_fmac_f32_e32 v76, v126, v61
	v_fmac_f32_e32 v76, v127, v62
	v_fmac_f32_e32 v76, v128, v63
	s_waitcnt lgkmcnt(2)
	v_fmac_f32_e32 v76, v129, v64
	v_fmac_f32_e32 v76, v130, v65
	v_fmac_f32_e32 v76, v131, v66
	v_fmac_f32_e32 v76, v132, v67
	s_waitcnt lgkmcnt(1)
	v_fmac_f32_e32 v76, v0, v68
	v_fmac_f32_e32 v76, v1, v69
	v_pk_mul_f32 v[60:61], v[2:3], v[70:71]
	s_nop 0
	v_add_f32_e32 v60, v76, v60
	v_add_f32_e32 v62, v60, v61
	s_waitcnt lgkmcnt(0)
	v_pk_mul_f32 v[60:61], v[4:5], v[72:73]
	s_nop 0
	v_add_f32_e32 v60, v62, v60
	v_add_f32_e32 v62, v60, v61
	v_pk_mul_f32 v[60:61], v[6:7], v[74:75]
	s_nop 0
	v_add_f32_e32 v60, v62, v60
	v_add_f32_e32 v60, v60, v61
	v_min_f32_e32 v61, 0, v60
	v_mul_f32_e64 v60, |v60|, s65
	v_exp_f32_e32 v60, v60
	s_nop 0
	v_add_f32_e32 v60, 1.0, v60
	v_cmp_gt_f32_e64 s[42:43], s80, v60
	s_nop 1
	v_cndmask_b32_e64 v62, 0, 32, s[42:43]
	v_ldexp_f32 v60, v60, v62
	v_log_f32_e32 v60, v60
	s_nop 0
	v_mul_f32_e32 v62, 0x3f317217, v60
	v_fma_f32 v62, v60, s81, -v62
	v_fmac_f32_e32 v62, 0x3377d1cf, v60
	v_fmac_f32_e32 v62, 0x3f317217, v60
	v_cmp_lt_f32_e64 s[44:45], |v60|, s71
	s_nop 1
	v_cndmask_b32_e64 v60, v60, v62, s[44:45]
	v_cndmask_b32_e64 v62, 0, v236, s[42:43]
	v_sub_f32_e32 v60, v60, v62
	v_sub_f32_e32 v60, v61, v60
	v_fmamk_f32 v89, v60, 0x3d800000, v59
	v_lshl_add_u64 v[60:61], v[12:13], 0, s[0:1]
	global_load_ushort v62, v[60:61], off
	s_lshl_b32 s0, s68, 6
	s_add_i32 s0, s0, 0x10000
	v_mov_b32_e32 v74, s0
	s_lshl_b64 s[0:1], s[82:83], 12
	s_waitcnt vmcnt(0)
	v_lshlrev_b32_e32 v90, 16, v62
	ds_read_b128 v[62:65], v74
	ds_read_b128 v[66:69], v74 offset:16
	ds_read_b128 v[70:73], v74 offset:32
	ds_read_b128 v[74:77], v74 offset:48
	s_waitcnt lgkmcnt(3)
	v_fma_f32 v78, v133, v62, v134
	v_fmac_f32_e32 v78, v126, v63
	v_fmac_f32_e32 v78, v127, v64
	v_fmac_f32_e32 v78, v128, v65
	s_waitcnt lgkmcnt(2)
	v_fmac_f32_e32 v78, v129, v66
	v_fmac_f32_e32 v78, v130, v67
	v_fmac_f32_e32 v78, v131, v68
	v_fmac_f32_e32 v78, v132, v69
	s_waitcnt lgkmcnt(1)
	v_fmac_f32_e32 v78, v0, v70
	v_fmac_f32_e32 v78, v1, v71
	v_pk_mul_f32 v[62:63], v[2:3], v[72:73]
	s_nop 0
	v_add_f32_e32 v62, v78, v62
	v_add_f32_e32 v64, v62, v63
	s_waitcnt lgkmcnt(0)
	v_pk_mul_f32 v[62:63], v[4:5], v[74:75]
	s_nop 0
	v_add_f32_e32 v62, v64, v62
	v_add_f32_e32 v64, v62, v63
	v_pk_mul_f32 v[62:63], v[6:7], v[76:77]
	s_nop 0
	v_add_f32_e32 v62, v64, v62
	v_add_f32_e32 v62, v62, v63
	v_min_f32_e32 v63, 0, v62
	v_mul_f32_e64 v62, |v62|, s65
	v_exp_f32_e32 v62, v62
	s_nop 0
	v_add_f32_e32 v62, 1.0, v62
	v_cmp_gt_f32_e64 s[42:43], s80, v62
	s_nop 1
	v_cndmask_b32_e64 v64, 0, 32, s[42:43]
	v_ldexp_f32 v62, v62, v64
	v_log_f32_e32 v62, v62
	s_nop 0
	v_mul_f32_e32 v64, 0x3f317217, v62
	v_fma_f32 v64, v62, s81, -v64
	v_fmac_f32_e32 v64, 0x3377d1cf, v62
	v_fmac_f32_e32 v64, 0x3f317217, v62
	v_cmp_lt_f32_e64 s[44:45], |v62|, s71
	s_nop 1
	v_cndmask_b32_e64 v62, v62, v64, s[44:45]
	v_cndmask_b32_e64 v64, 0, v236, s[42:43]
	v_sub_f32_e32 v62, v62, v64
	v_sub_f32_e32 v62, v63, v62
	v_fmamk_f32 v91, v62, 0x3d800000, v89
	v_lshl_add_u64 v[62:63], v[12:13], 0, s[0:1]
	global_load_ushort v64, v[62:63], off
	s_lshl_b32 s0, s69, 6
	s_add_i32 s0, s0, 0x10000
	v_mov_b32_e32 v76, s0
	s_lshl_b64 s[0:1], s[96:97], 12
	s_waitcnt vmcnt(0)
	v_lshlrev_b32_e32 v136, 16, v64
	ds_read_b128 v[64:67], v76
	ds_read_b128 v[68:71], v76 offset:16
	ds_read_b128 v[72:75], v76 offset:32
	ds_read_b128 v[76:79], v76 offset:48
	s_waitcnt lgkmcnt(3)
	v_fma_f32 v80, v133, v64, v134
	v_fmac_f32_e32 v80, v126, v65
	v_fmac_f32_e32 v80, v127, v66
	v_fmac_f32_e32 v80, v128, v67
	s_waitcnt lgkmcnt(2)
	v_fmac_f32_e32 v80, v129, v68
	v_fmac_f32_e32 v80, v130, v69
	v_fmac_f32_e32 v80, v131, v70
	v_fmac_f32_e32 v80, v132, v71
	s_waitcnt lgkmcnt(1)
	v_fmac_f32_e32 v80, v0, v72
	v_fmac_f32_e32 v80, v1, v73
	v_pk_mul_f32 v[64:65], v[2:3], v[74:75]
	s_nop 0
	v_add_f32_e32 v64, v80, v64
	v_add_f32_e32 v66, v64, v65
	s_waitcnt lgkmcnt(0)
	v_pk_mul_f32 v[64:65], v[4:5], v[76:77]
	s_nop 0
	v_add_f32_e32 v64, v66, v64
	v_add_f32_e32 v66, v64, v65
	v_pk_mul_f32 v[64:65], v[6:7], v[78:79]
	s_nop 0
	v_add_f32_e32 v64, v66, v64
	v_add_f32_e32 v64, v64, v65
	v_min_f32_e32 v65, 0, v64
	v_mul_f32_e64 v64, |v64|, s65
	v_exp_f32_e32 v64, v64
	s_nop 0
	v_add_f32_e32 v64, 1.0, v64
	v_cmp_gt_f32_e64 s[42:43], s80, v64
	s_nop 1
	v_cndmask_b32_e64 v66, 0, 32, s[42:43]
	v_ldexp_f32 v64, v64, v66
	v_log_f32_e32 v64, v64
	s_nop 0
	v_mul_f32_e32 v66, 0x3f317217, v64
	v_fma_f32 v66, v64, s81, -v66
	v_fmac_f32_e32 v66, 0x3377d1cf, v64
	v_fmac_f32_e32 v66, 0x3f317217, v64
	v_cmp_lt_f32_e64 s[44:45], |v64|, s71
	s_nop 1
	v_cndmask_b32_e64 v64, v64, v66, s[44:45]
	v_cndmask_b32_e64 v66, 0, v236, s[42:43]
	v_sub_f32_e32 v64, v64, v66
	v_sub_f32_e32 v64, v65, v64
	v_fmamk_f32 v137, v64, 0x3d800000, v91
	v_lshl_add_u64 v[64:65], v[12:13], 0, s[0:1]
	global_load_ushort v66, v[64:65], off
	s_lshl_b32 s0, s10, 6
	s_add_i32 s0, s0, 0x10000
	v_mov_b32_e32 v78, s0
	s_lshl_b64 s[0:1], s[8:9], 12
	s_lshl_b64 s[8:9], s[8:9], 11
	s_waitcnt vmcnt(0)
	v_lshlrev_b32_e32 v138, 16, v66
	ds_read_b128 v[66:69], v78
	ds_read_b128 v[70:73], v78 offset:16
	ds_read_b128 v[74:77], v78 offset:32
	ds_read_b128 v[78:81], v78 offset:48
	s_waitcnt lgkmcnt(3)
	v_fma_f32 v82, v133, v66, v134
	v_fmac_f32_e32 v82, v126, v67
	v_fmac_f32_e32 v82, v127, v68
	v_fmac_f32_e32 v82, v128, v69
	s_waitcnt lgkmcnt(2)
	v_fmac_f32_e32 v82, v129, v70
	v_fmac_f32_e32 v82, v130, v71
	v_fmac_f32_e32 v82, v131, v72
	v_fmac_f32_e32 v82, v132, v73
	s_waitcnt lgkmcnt(1)
	v_fmac_f32_e32 v82, v0, v74
	v_fmac_f32_e32 v82, v1, v75
	v_pk_mul_f32 v[66:67], v[2:3], v[76:77]
	s_nop 0
	v_add_f32_e32 v66, v82, v66
	v_add_f32_e32 v68, v66, v67
	s_waitcnt lgkmcnt(0)
	v_pk_mul_f32 v[66:67], v[4:5], v[78:79]
	s_nop 0
	v_add_f32_e32 v66, v68, v66
	v_add_f32_e32 v68, v66, v67
	v_pk_mul_f32 v[66:67], v[6:7], v[80:81]
	s_nop 0
	v_add_f32_e32 v66, v68, v66
	v_add_f32_e32 v66, v66, v67
	v_min_f32_e32 v67, 0, v66
	v_mul_f32_e64 v66, |v66|, s65
	v_exp_f32_e32 v66, v66
	s_nop 0
	v_add_f32_e32 v66, 1.0, v66
	v_cmp_gt_f32_e64 s[42:43], s80, v66
	s_nop 1
	v_cndmask_b32_e64 v68, 0, 32, s[42:43]
	v_ldexp_f32 v66, v66, v68
	v_log_f32_e32 v66, v66
	s_nop 0
	v_mul_f32_e32 v68, 0x3f317217, v66
	v_fma_f32 v68, v66, s81, -v68
	v_fmac_f32_e32 v68, 0x3377d1cf, v66
	v_fmac_f32_e32 v68, 0x3f317217, v66
	v_cmp_lt_f32_e64 s[44:45], |v66|, s71
	s_nop 1
	v_cndmask_b32_e64 v66, v66, v68, s[44:45]
	v_cndmask_b32_e64 v68, 0, v236, s[42:43]
	v_sub_f32_e32 v66, v66, v68
	v_sub_f32_e32 v66, v67, v66
	v_fmamk_f32 v139, v66, 0x3d800000, v137
	v_lshl_add_u64 v[66:67], v[12:13], 0, s[0:1]
	global_load_ushort v68, v[66:67], off
	s_lshl_b32 s0, s11, 6
	s_add_i32 s0, s0, 0x10000
	v_mov_b32_e32 v80, s0
	s_lshl_b64 s[0:1], s[46:47], 12
	s_waitcnt vmcnt(0)
	v_lshlrev_b32_e32 v140, 16, v68
	ds_read_b128 v[68:71], v80
	ds_read_b128 v[72:75], v80 offset:16
	ds_read_b128 v[76:79], v80 offset:32
	ds_read_b128 v[80:83], v80 offset:48
	s_waitcnt lgkmcnt(3)
	v_fma_f32 v84, v133, v68, v134
	v_fmac_f32_e32 v84, v126, v69
	v_fmac_f32_e32 v84, v127, v70
	v_fmac_f32_e32 v84, v128, v71
	s_waitcnt lgkmcnt(2)
	v_fmac_f32_e32 v84, v129, v72
	v_fmac_f32_e32 v84, v130, v73
	v_fmac_f32_e32 v84, v131, v74
	v_fmac_f32_e32 v84, v132, v75
	s_waitcnt lgkmcnt(1)
	v_fmac_f32_e32 v84, v0, v76
	v_fmac_f32_e32 v84, v1, v77
	v_pk_mul_f32 v[68:69], v[2:3], v[78:79]
	s_nop 0
	v_add_f32_e32 v68, v84, v68
	v_add_f32_e32 v70, v68, v69
	s_waitcnt lgkmcnt(0)
	v_pk_mul_f32 v[68:69], v[4:5], v[80:81]
	s_nop 0
	v_add_f32_e32 v68, v70, v68
	v_add_f32_e32 v70, v68, v69
	v_pk_mul_f32 v[68:69], v[6:7], v[82:83]
	s_nop 0
	v_add_f32_e32 v68, v70, v68
	v_add_f32_e32 v68, v68, v69
	v_min_f32_e32 v69, 0, v68
	v_mul_f32_e64 v68, |v68|, s65
	v_exp_f32_e32 v68, v68
	s_nop 0
	v_add_f32_e32 v68, 1.0, v68
	v_cmp_gt_f32_e64 s[42:43], s80, v68
	s_nop 1
	v_cndmask_b32_e64 v70, 0, 32, s[42:43]
	v_ldexp_f32 v68, v68, v70
	v_log_f32_e32 v68, v68
	s_nop 0
	v_mul_f32_e32 v70, 0x3f317217, v68
	v_fma_f32 v70, v68, s81, -v70
	v_fmac_f32_e32 v70, 0x3377d1cf, v68
	v_fmac_f32_e32 v70, 0x3f317217, v68
	v_cmp_lt_f32_e64 s[44:45], |v68|, s71
	s_nop 1
	v_cndmask_b32_e64 v68, v68, v70, s[44:45]
	v_cndmask_b32_e64 v70, 0, v236, s[42:43]
	v_sub_f32_e32 v68, v68, v70
	v_sub_f32_e32 v68, v69, v68
	v_fmamk_f32 v141, v68, 0x3d800000, v139
	v_lshl_add_u64 v[68:69], v[12:13], 0, s[0:1]
	global_load_ushort v70, v[68:69], off
	s_lshl_b32 s0, s12, 6
	s_add_i32 s0, s0, 0x10000
	v_mov_b32_e32 v82, s0
	s_lshl_b64 s[0:1], s[60:61], 12
	s_waitcnt vmcnt(0)
	v_lshlrev_b32_e32 v142, 16, v70
	ds_read_b128 v[70:73], v82
	ds_read_b128 v[74:77], v82 offset:16
	ds_read_b128 v[78:81], v82 offset:32
	ds_read_b128 v[82:85], v82 offset:48
	s_waitcnt lgkmcnt(3)
	v_fma_f32 v86, v133, v70, v134
	v_fmac_f32_e32 v86, v126, v71
	v_fmac_f32_e32 v86, v127, v72
	v_fmac_f32_e32 v86, v128, v73
	s_waitcnt lgkmcnt(2)
	v_fmac_f32_e32 v86, v129, v74
	v_fmac_f32_e32 v86, v130, v75
	v_fmac_f32_e32 v86, v131, v76
	v_fmac_f32_e32 v86, v132, v77
	s_waitcnt lgkmcnt(1)
	v_fmac_f32_e32 v86, v0, v78
	v_fmac_f32_e32 v86, v1, v79
	v_pk_mul_f32 v[70:71], v[2:3], v[80:81]
	s_nop 0
	v_add_f32_e32 v70, v86, v70
	v_add_f32_e32 v72, v70, v71
	s_waitcnt lgkmcnt(0)
	v_pk_mul_f32 v[70:71], v[4:5], v[82:83]
	s_nop 0
	v_add_f32_e32 v70, v72, v70
	v_add_f32_e32 v72, v70, v71
	v_pk_mul_f32 v[70:71], v[6:7], v[84:85]
	s_nop 0
	v_add_f32_e32 v70, v72, v70
	v_add_f32_e32 v70, v70, v71
	v_min_f32_e32 v71, 0, v70
	v_mul_f32_e64 v70, |v70|, s65
	v_exp_f32_e32 v70, v70
	s_nop 0
	v_add_f32_e32 v70, 1.0, v70
	v_cmp_gt_f32_e64 s[42:43], s80, v70
	s_nop 1
	v_cndmask_b32_e64 v72, 0, 32, s[42:43]
	v_ldexp_f32 v70, v70, v72
	v_log_f32_e32 v70, v70
	s_nop 0
	v_mul_f32_e32 v72, 0x3f317217, v70
	v_fma_f32 v72, v70, s81, -v72
	v_fmac_f32_e32 v72, 0x3377d1cf, v70
	v_fmac_f32_e32 v72, 0x3f317217, v70
	v_cmp_lt_f32_e64 s[44:45], |v70|, s71
	s_nop 1
	v_cndmask_b32_e64 v70, v70, v72, s[44:45]
	v_cndmask_b32_e64 v72, 0, v236, s[42:43]
	v_sub_f32_e32 v70, v70, v72
	v_sub_f32_e32 v70, v71, v70
	v_fmamk_f32 v143, v70, 0x3d800000, v141
	v_lshl_add_u64 v[70:71], v[12:13], 0, s[0:1]
	global_load_ushort v72, v[70:71], off
	s_lshl_b32 s0, s13, 6
	s_add_i32 s0, s0, 0x10000
	v_mov_b32_e32 v84, s0
	s_lshl_b64 s[0:1], s[62:63], 12
	s_waitcnt vmcnt(0)
	v_lshlrev_b32_e32 v144, 16, v72
	ds_read_b128 v[72:75], v84
	ds_read_b128 v[76:79], v84 offset:16
	ds_read_b128 v[80:83], v84 offset:32
	ds_read_b128 v[84:87], v84 offset:48
	s_waitcnt lgkmcnt(3)
	v_fma_f32 v135, v133, v72, v134
	v_fmac_f32_e32 v135, v126, v73
	v_fmac_f32_e32 v135, v127, v74
	v_fmac_f32_e32 v135, v128, v75
	s_waitcnt lgkmcnt(2)
	v_fmac_f32_e32 v135, v129, v76
	v_fmac_f32_e32 v135, v130, v77
	v_fmac_f32_e32 v135, v131, v78
	v_fmac_f32_e32 v135, v132, v79
	s_waitcnt lgkmcnt(1)
	v_fmac_f32_e32 v135, v0, v80
	v_fmac_f32_e32 v135, v1, v81
	v_pk_mul_f32 v[72:73], v[2:3], v[82:83]
	s_nop 0
	v_add_f32_e32 v72, v135, v72
	v_add_f32_e32 v74, v72, v73
	s_waitcnt lgkmcnt(0)
	v_pk_mul_f32 v[72:73], v[4:5], v[84:85]
	s_nop 0
	v_add_f32_e32 v72, v74, v72
	v_add_f32_e32 v74, v72, v73
	v_pk_mul_f32 v[72:73], v[6:7], v[86:87]
	s_nop 0
	v_add_f32_e32 v72, v74, v72
	v_add_f32_e32 v72, v72, v73
	v_min_f32_e32 v73, 0, v72
	v_mul_f32_e64 v72, |v72|, s65
	v_exp_f32_e32 v72, v72
	s_nop 0
	v_add_f32_e32 v72, 1.0, v72
	v_cmp_gt_f32_e64 s[42:43], s80, v72
	s_nop 1
	v_cndmask_b32_e64 v74, 0, 32, s[42:43]
	v_ldexp_f32 v72, v72, v74
	v_log_f32_e32 v72, v72
	s_nop 0
	v_mul_f32_e32 v74, 0x3f317217, v72
	v_fma_f32 v74, v72, s81, -v74
	v_fmac_f32_e32 v74, 0x3377d1cf, v72
	v_fmac_f32_e32 v74, 0x3f317217, v72
	v_cmp_lt_f32_e64 s[44:45], |v72|, s71
	s_nop 1
	v_cndmask_b32_e64 v72, v72, v74, s[44:45]
	v_cndmask_b32_e64 v74, 0, v236, s[42:43]
	v_sub_f32_e32 v72, v72, v74
	v_sub_f32_e32 v72, v73, v72
	v_fmamk_f32 v145, v72, 0x3d800000, v143
	v_lshl_add_u64 v[72:73], v[12:13], 0, s[0:1]
	global_load_ushort v74, v[72:73], off
	s_lshl_b32 s0, s14, 6
	s_add_i32 s0, s0, 0x10000
	v_mov_b32_e32 v86, s0
	s_lshl_b64 s[0:1], s[56:57], 12
	s_waitcnt vmcnt(0)
	v_lshlrev_b32_e32 v146, 16, v74
	ds_read_b128 v[74:77], v86
	ds_read_b128 v[78:81], v86 offset:16
	ds_read_b128 v[82:85], v86 offset:32
	ds_read_b128 v[148:151], v86 offset:48
	s_waitcnt lgkmcnt(3)
	v_fma_f32 v86, v133, v74, v134
	v_fmac_f32_e32 v86, v126, v75
	v_fmac_f32_e32 v86, v127, v76
	v_fmac_f32_e32 v86, v128, v77
	s_waitcnt lgkmcnt(2)
	v_fmac_f32_e32 v86, v129, v78
	v_fmac_f32_e32 v86, v130, v79
	v_fmac_f32_e32 v86, v131, v80
	v_fmac_f32_e32 v86, v132, v81
	s_waitcnt lgkmcnt(1)
	v_fmac_f32_e32 v86, v0, v82
	v_fmac_f32_e32 v86, v1, v83
	v_pk_mul_f32 v[74:75], v[2:3], v[84:85]
	s_nop 0
	v_add_f32_e32 v74, v86, v74
	v_add_f32_e32 v76, v74, v75
	s_waitcnt lgkmcnt(0)
	v_pk_mul_f32 v[74:75], v[4:5], v[148:149]
	s_nop 0
	v_add_f32_e32 v74, v76, v74
	v_add_f32_e32 v76, v74, v75
	v_pk_mul_f32 v[74:75], v[6:7], v[150:151]
	s_nop 0
	v_add_f32_e32 v74, v76, v74
	v_add_f32_e32 v74, v74, v75
	v_min_f32_e32 v75, 0, v74
	v_mul_f32_e64 v74, |v74|, s65
	v_exp_f32_e32 v74, v74
	s_nop 0
	v_add_f32_e32 v74, 1.0, v74
	v_cmp_gt_f32_e64 s[42:43], s80, v74
	s_nop 1
	v_cndmask_b32_e64 v76, 0, 32, s[42:43]
	v_ldexp_f32 v74, v74, v76
	v_log_f32_e32 v74, v74
	s_nop 0
	v_mul_f32_e32 v76, 0x3f317217, v74
	v_fma_f32 v76, v74, s81, -v76
	v_fmac_f32_e32 v76, 0x3377d1cf, v74
	v_fmac_f32_e32 v76, 0x3f317217, v74
	v_cmp_lt_f32_e64 s[44:45], |v74|, s71
	s_nop 1
	v_cndmask_b32_e64 v74, v74, v76, s[44:45]
	v_cndmask_b32_e64 v76, 0, v236, s[42:43]
	v_sub_f32_e32 v74, v74, v76
	v_sub_f32_e32 v74, v75, v74
	v_fmamk_f32 v147, v74, 0x3d800000, v145
	v_lshl_add_u64 v[74:75], v[12:13], 0, s[0:1]
	global_load_ushort v76, v[74:75], off
	s_lshl_b32 s0, s15, 6
	s_add_i32 s0, s0, 0x10000
	v_mov_b32_e32 v135, s0
	s_or_b32 s0, s15, s72
	s_ashr_i32 s1, s0, 31
	s_lshl_b64 s[4:5], s[0:1], 12
	v_cvt_pk_bf16_f32 v160, v160, s0
	s_waitcnt vmcnt(0)
	v_lshlrev_b32_e32 v148, 16, v76
	ds_read_b128 v[76:79], v135
	ds_read_b128 v[80:83], v135 offset:16
	ds_read_b128 v[84:87], v135 offset:32
	ds_read_b128 v[150:153], v135 offset:48
	s_waitcnt lgkmcnt(3)
	v_fma_f32 v135, v133, v76, v134
	v_fmac_f32_e32 v135, v126, v77
	v_fmac_f32_e32 v135, v127, v78
	v_fmac_f32_e32 v135, v128, v79
	s_waitcnt lgkmcnt(2)
	v_fmac_f32_e32 v135, v129, v80
	v_fmac_f32_e32 v135, v130, v81
	v_fmac_f32_e32 v135, v131, v82
	v_fmac_f32_e32 v135, v132, v83
	s_waitcnt lgkmcnt(1)
	v_fmac_f32_e32 v135, v0, v84
	v_fmac_f32_e32 v135, v1, v85
	v_pk_mul_f32 v[76:77], v[2:3], v[86:87]
	s_nop 0
	v_add_f32_e32 v76, v135, v76
	v_add_f32_e32 v78, v76, v77
	s_waitcnt lgkmcnt(0)
	v_pk_mul_f32 v[76:77], v[4:5], v[150:151]
	s_nop 0
	v_add_f32_e32 v76, v78, v76
	v_add_f32_e32 v78, v76, v77
	v_pk_mul_f32 v[76:77], v[6:7], v[152:153]
	s_nop 0
	v_add_f32_e32 v76, v78, v76
	v_add_f32_e32 v76, v76, v77
	v_min_f32_e32 v77, 0, v76
	v_mul_f32_e64 v76, |v76|, s65
	v_exp_f32_e32 v76, v76
	s_nop 0
	v_add_f32_e32 v76, 1.0, v76
	v_cmp_gt_f32_e64 s[42:43], s80, v76
	s_nop 1
	v_cndmask_b32_e64 v78, 0, 32, s[42:43]
	v_ldexp_f32 v76, v76, v78
	v_log_f32_e32 v76, v76
	s_nop 0
	v_mul_f32_e32 v78, 0x3f317217, v76
	v_fma_f32 v78, v76, s81, -v78
	v_fmac_f32_e32 v78, 0x3377d1cf, v76
	v_fmac_f32_e32 v78, 0x3f317217, v76
	v_cmp_lt_f32_e64 s[44:45], |v76|, s71
	s_nop 1
	v_cndmask_b32_e64 v76, v76, v78, s[44:45]
	v_cndmask_b32_e64 v78, 0, v236, s[42:43]
	v_sub_f32_e32 v76, v76, v78
	v_sub_f32_e32 v76, v77, v76
	v_fmamk_f32 v149, v76, 0x3d800000, v147
	v_lshl_add_u64 v[76:77], v[12:13], 0, s[4:5]
	global_load_ushort v78, v[76:77], off
	s_lshl_b32 s4, s16, 6
	s_add_i32 s4, s4, 0x10000
	v_mov_b32_e32 v86, s4
	s_lshl_b64 s[4:5], s[6:7], 12
	s_waitcnt vmcnt(0)
	v_lshlrev_b32_e32 v150, 16, v78
	ds_read_b128 v[78:81], v86
	ds_read_b128 v[82:85], v86 offset:16
	ds_read_b128 v[152:155], v86 offset:32
	ds_read_b128 v[156:159], v86 offset:48
	s_waitcnt lgkmcnt(3)
	v_fma_f32 v86, v133, v78, v134
	v_fmac_f32_e32 v86, v126, v79
	v_fmac_f32_e32 v86, v127, v80
	v_fmac_f32_e32 v86, v128, v81
	s_waitcnt lgkmcnt(2)
	v_fmac_f32_e32 v86, v129, v82
	v_fmac_f32_e32 v86, v130, v83
	v_fmac_f32_e32 v86, v131, v84
	v_fmac_f32_e32 v86, v132, v85
	s_waitcnt lgkmcnt(1)
	v_fmac_f32_e32 v86, v0, v152
	v_fmac_f32_e32 v86, v1, v153
	v_pk_mul_f32 v[78:79], v[2:3], v[154:155]
	s_nop 0
	v_add_f32_e32 v78, v86, v78
	v_add_f32_e32 v80, v78, v79
	s_waitcnt lgkmcnt(0)
	v_pk_mul_f32 v[78:79], v[4:5], v[156:157]
	s_nop 0
	v_add_f32_e32 v78, v80, v78
	v_add_f32_e32 v80, v78, v79
	v_pk_mul_f32 v[78:79], v[6:7], v[158:159]
	s_nop 0
	v_add_f32_e32 v78, v80, v78
	v_add_f32_e32 v78, v78, v79
	v_min_f32_e32 v79, 0, v78
	v_mul_f32_e64 v78, |v78|, s65
	v_exp_f32_e32 v78, v78
	s_nop 0
	v_add_f32_e32 v78, 1.0, v78
	v_cmp_gt_f32_e64 s[42:43], s80, v78
	s_nop 1
	v_cndmask_b32_e64 v80, 0, 32, s[42:43]
	v_ldexp_f32 v78, v78, v80
	v_log_f32_e32 v78, v78
	s_nop 0
	v_mul_f32_e32 v80, 0x3f317217, v78
	v_fma_f32 v80, v78, s81, -v80
	v_fmac_f32_e32 v80, 0x3377d1cf, v78
	v_fmac_f32_e32 v80, 0x3f317217, v78
	v_cmp_lt_f32_e64 s[44:45], |v78|, s71
	s_nop 1
	v_cndmask_b32_e64 v78, v78, v80, s[44:45]
	v_cndmask_b32_e64 v80, 0, v236, s[42:43]
	v_sub_f32_e32 v78, v78, v80
	v_sub_f32_e32 v78, v79, v78
	v_fmamk_f32 v151, v78, 0x3d800000, v149
	v_lshl_add_u64 v[78:79], v[12:13], 0, s[4:5]
	global_load_ushort v80, v[78:79], off
	s_lshl_b32 s4, s17, 6
	s_add_i32 s4, s4, 0x10000
	v_mov_b32_e32 v135, s4
	s_lshl_b64 s[4:5], s[54:55], 12
	s_waitcnt vmcnt(0)
	v_lshlrev_b32_e32 v152, 16, v80
	ds_read_b128 v[80:83], v135
	ds_read_b128 v[84:87], v135 offset:16
	ds_read_b128 v[154:157], v135 offset:32
	ds_read_b128 v[162:165], v135 offset:48
	s_waitcnt lgkmcnt(3)
	v_fma_f32 v135, v133, v80, v134
	v_fmac_f32_e32 v135, v126, v81
	v_fmac_f32_e32 v135, v127, v82
	v_fmac_f32_e32 v135, v128, v83
	s_waitcnt lgkmcnt(2)
	v_fmac_f32_e32 v135, v129, v84
	v_fmac_f32_e32 v135, v130, v85
	v_fmac_f32_e32 v135, v131, v86
	v_fmac_f32_e32 v135, v132, v87
	s_waitcnt lgkmcnt(1)
	v_fmac_f32_e32 v135, v0, v154
	v_fmac_f32_e32 v135, v1, v155
	v_pk_mul_f32 v[80:81], v[2:3], v[156:157]
	s_nop 0
	v_add_f32_e32 v80, v135, v80
	v_add_f32_e32 v82, v80, v81
	s_waitcnt lgkmcnt(0)
	v_pk_mul_f32 v[80:81], v[4:5], v[162:163]
	s_nop 0
	v_add_f32_e32 v80, v82, v80
	v_add_f32_e32 v82, v80, v81
	v_pk_mul_f32 v[80:81], v[6:7], v[164:165]
	s_nop 0
	v_add_f32_e32 v80, v82, v80
	v_add_f32_e32 v80, v80, v81
	v_min_f32_e32 v81, 0, v80
	v_mul_f32_e64 v80, |v80|, s65
	v_exp_f32_e32 v80, v80
	s_nop 0
	v_add_f32_e32 v80, 1.0, v80
	v_cmp_gt_f32_e64 s[42:43], s80, v80
	s_nop 1
	v_cndmask_b32_e64 v82, 0, 32, s[42:43]
	v_ldexp_f32 v80, v80, v82
	v_log_f32_e32 v80, v80
	s_nop 0
	v_mul_f32_e32 v82, 0x3f317217, v80
	v_fma_f32 v82, v80, s81, -v82
	v_fmac_f32_e32 v82, 0x3377d1cf, v80
	v_fmac_f32_e32 v82, 0x3f317217, v80
	v_cmp_lt_f32_e64 s[44:45], |v80|, s71
	s_nop 1
	v_cndmask_b32_e64 v80, v80, v82, s[44:45]
	v_cndmask_b32_e64 v82, 0, v236, s[42:43]
	v_sub_f32_e32 v80, v80, v82
	v_sub_f32_e32 v80, v81, v80
	v_fmamk_f32 v153, v80, 0x3d800000, v151
	v_lshl_add_u64 v[80:81], v[12:13], 0, s[4:5]
	global_load_ushort v82, v[80:81], off
	s_lshl_b32 s4, s18, 6
	s_add_i32 s4, s4, 0x10000
	v_mov_b32_e32 v86, s4
	s_lshl_b64 s[4:5], s[48:49], 12
	s_waitcnt vmcnt(0)
	v_lshlrev_b32_e32 v154, 16, v82
	ds_read_b128 v[82:85], v86
	ds_read_b128 v[156:159], v86 offset:16
	ds_read_b128 v[162:165], v86 offset:32
	ds_read_b128 v[166:169], v86 offset:48
	s_waitcnt lgkmcnt(3)
	v_fma_f32 v86, v133, v82, v134
	v_fmac_f32_e32 v86, v126, v83
	v_fmac_f32_e32 v86, v127, v84
	v_fmac_f32_e32 v86, v128, v85
	s_waitcnt lgkmcnt(2)
	v_fmac_f32_e32 v86, v129, v156
	v_fmac_f32_e32 v86, v130, v157
	v_fmac_f32_e32 v86, v131, v158
	v_fmac_f32_e32 v86, v132, v159
	s_waitcnt lgkmcnt(1)
	v_fmac_f32_e32 v86, v0, v162
	v_fmac_f32_e32 v86, v1, v163
	v_pk_mul_f32 v[82:83], v[2:3], v[164:165]
	s_nop 0
	v_add_f32_e32 v82, v86, v82
	v_add_f32_e32 v84, v82, v83
	s_waitcnt lgkmcnt(0)
	v_pk_mul_f32 v[82:83], v[4:5], v[166:167]
	s_nop 0
	v_add_f32_e32 v82, v84, v82
	v_add_f32_e32 v84, v82, v83
	v_pk_mul_f32 v[82:83], v[6:7], v[168:169]
	s_nop 0
	v_add_f32_e32 v82, v84, v82
	v_add_f32_e32 v82, v82, v83
	v_min_f32_e32 v83, 0, v82
	v_mul_f32_e64 v82, |v82|, s65
	v_exp_f32_e32 v82, v82
	s_nop 0
	v_add_f32_e32 v82, 1.0, v82
	v_cmp_gt_f32_e64 s[42:43], s80, v82
	s_nop 1
	v_cndmask_b32_e64 v84, 0, 32, s[42:43]
	v_ldexp_f32 v82, v82, v84
	v_log_f32_e32 v82, v82
	s_nop 0
	v_mul_f32_e32 v84, 0x3f317217, v82
	v_fma_f32 v84, v82, s81, -v84
	v_fmac_f32_e32 v84, 0x3377d1cf, v82
	v_fmac_f32_e32 v84, 0x3f317217, v82
	v_cmp_lt_f32_e64 s[44:45], |v82|, s71
	s_nop 1
	v_cndmask_b32_e64 v82, v82, v84, s[44:45]
	v_cndmask_b32_e64 v84, 0, v236, s[42:43]
	v_sub_f32_e32 v82, v82, v84
	v_sub_f32_e32 v82, v83, v82
	v_fmamk_f32 v155, v82, 0x3d800000, v153
	v_lshl_add_u64 v[82:83], v[12:13], 0, s[4:5]
	global_load_ushort v84, v[82:83], off
	s_lshl_b32 s4, s19, 6
	s_add_i32 s4, s4, 0x10000
	v_mov_b32_e32 v135, s4
	s_or_b32 s4, s19, s72
	s_ashr_i32 s5, s4, 31
	s_waitcnt vmcnt(0)
	v_lshlrev_b32_e32 v156, 16, v84
	ds_read_b128 v[84:87], v135
	ds_read_b128 v[162:165], v135 offset:16
	ds_read_b128 v[166:169], v135 offset:32
	ds_read_b128 v[170:173], v135 offset:48
	s_waitcnt lgkmcnt(3)
	v_fma_f32 v135, v133, v84, v134
	v_fmac_f32_e32 v135, v126, v85
	v_fmac_f32_e32 v135, v127, v86
	v_fmac_f32_e32 v135, v128, v87
	s_waitcnt lgkmcnt(2)
	v_fmac_f32_e32 v135, v129, v162
	v_fmac_f32_e32 v135, v130, v163
	v_fmac_f32_e32 v135, v131, v164
	v_fmac_f32_e32 v135, v132, v165
	s_waitcnt lgkmcnt(1)
	v_pk_mul_f32 v[84:85], v[0:1], v[166:167]
	s_nop 0
	v_add_f32_e32 v84, v135, v84
	v_add_f32_e32 v86, v84, v85
	v_pk_mul_f32 v[84:85], v[2:3], v[168:169]
	s_nop 0
	v_add_f32_e32 v84, v86, v84
	v_add_f32_e32 v86, v84, v85
	s_waitcnt lgkmcnt(0)
	v_pk_mul_f32 v[84:85], v[4:5], v[170:171]
	s_nop 0
	v_add_f32_e32 v84, v86, v84
	v_add_f32_e32 v86, v84, v85
	v_pk_mul_f32 v[84:85], v[6:7], v[172:173]
	s_nop 0
	v_add_f32_e32 v84, v86, v84
	v_add_f32_e32 v84, v84, v85
	v_min_f32_e32 v85, 0, v84
	v_mul_f32_e64 v84, |v84|, s65
	v_exp_f32_e32 v84, v84
	s_nop 0
	v_add_f32_e32 v84, 1.0, v84
	v_cmp_gt_f32_e64 s[42:43], s80, v84
	s_nop 1
	v_cndmask_b32_e64 v86, 0, 32, s[42:43]
	v_ldexp_f32 v84, v84, v86
	v_log_f32_e32 v84, v84
	s_nop 0
	v_mul_f32_e32 v86, 0x3f317217, v84
	v_fma_f32 v86, v84, s81, -v86
	v_fmac_f32_e32 v86, 0x3377d1cf, v84
	v_fmac_f32_e32 v86, 0x3f317217, v84
	v_cmp_lt_f32_e64 s[44:45], |v84|, s71
	s_nop 1
	v_cndmask_b32_e64 v84, v84, v86, s[44:45]
	v_cndmask_b32_e64 v86, 0, v236, s[42:43]
	v_sub_f32_e32 v84, v84, v86
	v_sub_f32_e32 v84, v85, v84
	s_lshl_b64 s[42:43], s[4:5], 12
	v_fmamk_f32 v157, v84, 0x3d800000, v155
	v_lshl_add_u64 v[84:85], v[12:13], 0, s[42:43]
	global_load_ushort v86, v[84:85], off
	s_waitcnt vmcnt(0)
	v_lshlrev_b32_e32 v158, 16, v86
	v_mov_b32_e32 v86, s21
	ds_read_b128 v[162:165], v86
	ds_read_b128 v[166:169], v86 offset:16
	ds_read_b128 v[170:173], v86 offset:32
	ds_read_b128 v[174:177], v86 offset:48
	s_waitcnt lgkmcnt(3)
	v_fma_f32 v135, v133, v162, v134
	v_fmac_f32_e32 v135, v126, v163
	v_fmac_f32_e32 v135, v127, v164
	v_fmac_f32_e32 v135, v128, v165
	s_waitcnt lgkmcnt(2)
	v_fmac_f32_e32 v135, v129, v166
	v_fmac_f32_e32 v135, v130, v167
	v_fmac_f32_e32 v135, v131, v168
	v_fmac_f32_e32 v135, v132, v169
	s_waitcnt lgkmcnt(1)
	v_pk_mul_f32 v[86:87], v[0:1], v[170:171]
	s_nop 0
	v_add_f32_e32 v86, v135, v86
	v_add_f32_e32 v135, v86, v87
	v_pk_mul_f32 v[86:87], v[2:3], v[172:173]
	v_lshl_add_u32 v173, s3, 13, v93
	v_add_f32_e32 v86, v135, v86
	v_add_f32_e32 v135, v86, v87
	s_waitcnt lgkmcnt(0)
	v_pk_mul_f32 v[86:87], v[4:5], v[174:175]
	s_nop 0
	v_add_f32_e32 v86, v135, v86
	v_add_f32_e32 v135, v86, v87
	v_pk_mul_f32 v[86:87], v[6:7], v[176:177]
	s_nop 0
	v_add_f32_e32 v86, v135, v86
	v_add_f32_e32 v86, v86, v87
	v_min_f32_e32 v87, 0, v86
	v_mul_f32_e64 v86, |v86|, s65
	v_exp_f32_e32 v86, v86
	s_nop 0
	v_add_f32_e32 v86, 1.0, v86
	v_cmp_gt_f32_e64 s[42:43], s80, v86
	s_nop 1
	v_cndmask_b32_e64 v135, 0, 32, s[42:43]
	v_ldexp_f32 v86, v86, v135
	v_log_f32_e32 v86, v86
	s_nop 0
	v_mul_f32_e32 v135, 0x3f317217, v86
	v_fma_f32 v135, v86, s81, -v135
	v_fmac_f32_e32 v135, 0x3377d1cf, v86
	v_fmac_f32_e32 v135, 0x3f317217, v86
	v_cmp_lt_f32_e64 s[44:45], |v86|, s71
	s_nop 1
	v_cndmask_b32_e64 v86, v86, v135, s[44:45]
	v_cndmask_b32_e64 v135, 0, v236, s[42:43]
	s_or_b32 s42, s20, s72
	v_sub_f32_e32 v86, v86, v135
	s_ashr_i32 s43, s42, 31
	v_sub_f32_e32 v86, v87, v86
	s_lshl_b64 s[44:45], s[42:43], 12
	v_fmamk_f32 v135, v86, 0x3d800000, v157
	v_lshl_add_u64 v[86:87], v[12:13], 0, s[44:45]
	global_load_ushort v159, v[86:87], off
	global_load_ushort v174, v[60:61], off offset:2048
	global_load_ushort v176, v[14:15], off offset:2048
	global_load_ushort v175, v[56:57], off offset:2048
	global_load_ushort v177, v[62:63], off offset:2048
	global_load_ushort v169, v[64:65], off offset:2048
	global_load_ushort v171, v[68:69], off offset:2048
	global_load_ushort v170, v[66:67], off offset:2048
	global_load_ushort v172, v[70:71], off offset:2048
	global_load_ushort v165, v[72:73], off offset:2048
	global_load_ushort v167, v[76:77], off offset:2048
	global_load_ushort v166, v[74:75], off offset:2048
	global_load_ushort v168, v[78:79], off offset:2048
	global_load_ushort v161, v[80:81], off offset:2048
	global_load_ushort v163, v[84:85], off offset:2048
	global_load_ushort v162, v[82:83], off offset:2048
	global_load_ushort v164, v[86:87], off offset:2048
	s_lshl_b64 s[44:45], s[50:51], 11
	v_lshl_add_u64 v[14:15], v[8:9], 0, s[44:45]
	global_store_short v[14:15], v160, off
	v_mul_f32_e32 v15, 0x3fb8aa3b, v59
	v_exp_f32_e32 v15, v15
	v_mul_f32_e32 v14, 0x3d800000, v88
	s_lshl_b64 s[44:45], s[74:75], 11
	v_lshl_add_u64 v[56:57], v[8:9], 0, s[44:45]
	v_mul_f32_e32 v15, v14, v15
	v_cvt_pk_bf16_f32 v178, v15, s0
	global_store_short v[56:57], v178, off
	v_mul_f32_e32 v56, 0x3fb8aa3b, v89
	v_exp_f32_e32 v56, v56
	v_mul_f32_e32 v15, 0x3d800000, v90
	s_lshl_b64 s[44:45], s[76:77], 11
	v_mul_f32_e32 v14, 0xbfb8aa3b, v59
	v_mul_f32_e32 v15, v15, v56
	v_mul_f32_e32 v56, 0xbfb8aa3b, v89
	v_exp_f32_e32 v59, v56
	v_cvt_pk_bf16_f32 v180, v15, s0
	v_lshl_add_u64 v[56:57], v[8:9], 0, s[44:45]
	global_store_short v[56:57], v180, off
	v_mul_f32_e32 v56, 0x3fb8aa3b, v91
	v_exp_f32_e32 v56, v56
	v_mul_f32_e32 v15, 0x3d800000, v136
	s_lshl_b64 s[44:45], s[82:83], 11
	v_mul_f32_e32 v62, 0x3fb8aa3b, v143
	v_mul_f32_e32 v56, v15, v56
	v_cvt_pk_bf16_f32 v182, v56, s0
	v_lshl_add_u64 v[56:57], v[8:9], 0, s[44:45]
	global_store_short v[56:57], v182, off
	v_mul_f32_e32 v57, 0x3fb8aa3b, v137
	v_exp_f32_e32 v57, v57
	v_mul_f32_e32 v56, 0x3d800000, v138
	s_lshl_b64 s[44:45], s[96:97], 11
	v_lshl_add_u64 v[60:61], v[8:9], 0, s[44:45]
	v_mul_f32_e32 v57, v56, v57
	v_cvt_pk_bf16_f32 v183, v57, s0
	global_store_short v[60:61], v183, off
	v_mul_f32_e32 v60, 0x3fb8aa3b, v139
	v_exp_f32_e32 v60, v60
	v_mul_f32_e32 v61, 0x3fb8aa3b, v141
	v_exp_f32_e32 v61, v61
	v_mul_f32_e32 v57, 0x3d800000, v140
	v_mul_f32_e32 v57, v57, v60
	v_exp_f32_e32 v62, v62
	v_cvt_pk_bf16_f32 v138, v57, s0
	v_mul_f32_e32 v57, 0x3d800000, v142
	v_mul_f32_e32 v63, 0x3fb8aa3b, v145
	v_mul_f32_e32 v61, v57, v61
	v_exp_f32_e32 v63, v63
	v_mul_f32_e32 v57, 0xbfb8aa3b, v141
	v_cvt_pk_bf16_f32 v141, v61, s0
	v_mul_f32_e32 v61, 0x3d800000, v144
	v_mul_f32_e32 v64, 0x3fb8aa3b, v147
	v_mul_f32_e32 v15, 0xbfb8aa3b, v91
	v_mul_f32_e32 v62, v61, v62
	v_exp_f32_e32 v64, v64
	v_exp_f32_e32 v14, v14
	v_exp_f32_e32 v15, v15
	v_cvt_pk_bf16_f32 v186, v62, s0
	v_mul_f32_e32 v62, 0x3d800000, v146
	v_mul_f32_e32 v65, 0x3fb8aa3b, v149
	v_mul_f32_e32 v63, v62, v63
	v_exp_f32_e32 v65, v65
	v_cvt_pk_bf16_f32 v193, v63, s0
	v_mul_f32_e32 v63, 0x3d800000, v148
	v_mul_f32_e32 v68, 0x3fb8aa3b, v151
	v_mul_f32_e32 v63, v63, v64
	v_exp_f32_e32 v68, v68
	s_waitcnt vmcnt(19)
	v_lshlrev_b32_e32 v194, 16, v176
	v_lshlrev_b32_e32 v195, 16, v174
	s_waitcnt vmcnt(17)
	v_lshlrev_b32_e32 v177, 16, v177
	v_lshlrev_b32_e32 v176, 16, v175
	v_mul_f32_e32 v56, 0xbfb8aa3b, v137
	v_mul_f32_e32 v61, 0xbfb8aa3b, v143
	v_cvt_pk_bf16_f32 v143, v63, s0
	v_mul_f32_e32 v63, 0x3d800000, v150
	v_mul_f32_e32 v69, 0x3fb8aa3b, v153
	v_pk_mul_f32 v[58:59], v[58:59], v[194:195]
	v_pk_mul_f32 v[14:15], v[14:15], v[176:177]
	v_exp_f32_e32 v56, v56
	v_mul_f32_e32 v60, 0xbfb8aa3b, v139
	v_exp_f32_e32 v57, v57
	v_mul_f32_e32 v65, v63, v65
	v_exp_f32_e32 v69, v69
	v_cvt_pk_bf16_f32 v58, v58, v59
	v_cvt_pk_bf16_f32 v14, v14, v15
	ds_write_b16 v173, v160
	v_lshl_add_u32 v160, s66, 9, v111
	v_exp_f32_e32 v60, v60
	v_lshl_add_u64 v[66:67], v[8:9], 0, s[8:9]
	s_lshl_b64 s[8:9], s[46:47], 11
	v_exp_f32_e32 v61, v61
	v_cvt_pk_bf16_f32 v146, v65, s0
	v_mul_f32_e32 v65, 0x3d800000, v152
	v_mul_f32_e32 v72, 0x3fb8aa3b, v155
	v_lshrrev_b32_e32 v15, 16, v58
	v_lshrrev_b32_e32 v59, 16, v14
	v_lshl_add_u64 v[70:71], v[8:9], 0, s[8:9]
	s_lshl_b64 s[8:9], s[60:61], 11
	s_lshl_b64 s[0:1], s[0:1], 11
	v_mul_f32_e32 v68, v65, v68
	v_exp_f32_e32 v72, v72
	ds_write_b16 v173, v58 offset:32768
	ds_write_b16 v160, v178
	ds_write_b16 v160, v14 offset:32768
	ds_write_b16 v179, v180
	ds_write_b16 v179, v15 offset:32768
	ds_write_b16 v181, v182
	ds_write_b16 v181, v59 offset:32768
	v_and_b32_e32 v59, 0xffff0000, v14
	v_lshlrev_b32_e32 v14, 16, v14
	v_lshl_add_u32 v137, s69, 9, v114
	v_lshl_add_u64 v[76:77], v[8:9], 0, s[8:9]
	s_lshl_b64 s[8:9], s[62:63], 11
	v_cvt_pk_bf16_f32 v150, v68, s0
	v_mul_f32_e32 v68, 0x3d800000, v154
	v_mul_f32_e32 v73, 0x3fb8aa3b, v157
	v_or_b32_e32 v59, v59, v15
	v_or_b32_sdwa v58, v14, v58 dst_sel:DWORD dst_unused:UNUSED_PAD src0_sel:DWORD src1_sel:WORD_0
	s_waitcnt vmcnt(15)
	v_lshlrev_b32_e32 v15, 16, v171
	v_lshlrev_b32_e32 v14, 16, v169
	v_mul_f32_e32 v62, 0xbfb8aa3b, v145
	v_lshl_add_u64 v[80:81], v[8:9], 0, s[8:9]
	v_mul_f32_e32 v63, 0xbfb8aa3b, v149
	v_lshl_add_u64 v[78:79], v[8:9], 0, s[0:1]
	s_lshl_b64 s[0:1], s[6:7], 11
	v_mul_f32_e32 v69, v68, v69
	v_exp_f32_e32 v73, v73
	ds_write_b16 v137, v183
	global_store_short v[66:67], v138, off
	global_store_short v[70:71], v141, off
	global_store_short v[76:77], v186, off
	global_store_short v[80:81], v193, off
	s_waitcnt vmcnt(17)
	v_lshlrev_b32_e32 v67, 16, v172
	v_lshlrev_b32_e32 v66, 16, v170
	v_pk_mul_f32 v[14:15], v[56:57], v[14:15]
	v_exp_f32_e32 v62, v62
	v_mul_f32_e32 v64, 0xbfb8aa3b, v147
	v_exp_f32_e32 v63, v63
	v_mul_f32_e32 v65, 0xbfb8aa3b, v151
	v_cvt_pk_bf16_f32 v154, v69, s0
	v_mul_f32_e32 v69, 0x3d800000, v156
	v_mul_f32_e32 v90, 0x3fb8aa3b, v135
	v_cvt_pk_bf16_f32 v56, v14, v15
	v_pk_mul_f32 v[14:15], v[60:61], v[66:67]
	v_exp_f32_e32 v64, v64
	v_exp_f32_e32 v65, v65
	v_lshl_add_u64 v[84:85], v[8:9], 0, s[0:1]
	s_lshl_b64 s[0:1], s[54:55], 11
	v_mul_f32_e32 v69, v69, v72
	v_exp_f32_e32 v136, v90
	v_cvt_pk_bf16_f32 v14, v14, v15
	v_cvt_pk_bf16_f32 v148, v69, s0
	v_mul_f32_e32 v69, 0x3d800000, v158
	v_lshrrev_b32_e32 v15, 16, v14
	v_lshlrev_b32_e32 v159, 16, v159
	v_lshl_add_u32 v139, s10, 9, v115
	v_lshl_add_u32 v142, s11, 9, v116
	v_lshl_add_u32 v140, s13, 9, v118
	v_lshl_add_u64 v[88:89], v[8:9], 0, s[0:1]
	s_lshl_b64 s[0:1], s[48:49], 11
	v_mul_f32_e32 v73, v69, v73
	v_lshrrev_b32_e32 v57, 16, v56
	v_and_b32_e32 v60, 0xffff0000, v14
	v_lshlrev_b32_e32 v66, 16, v14
	ds_write_b16 v137, v56 offset:32768
	ds_write_b16 v139, v138
	ds_write_b16 v139, v14 offset:32768
	ds_write_b16 v142, v141
	ds_write_b16 v142, v57 offset:32768
	ds_write_b16 v192, v186
	ds_write_b16 v192, v15 offset:32768
	ds_write_b16 v140, v193
	s_waitcnt vmcnt(15)
	v_lshlrev_b32_e32 v15, 16, v167
	v_lshlrev_b32_e32 v14, 16, v165
	v_mul_f32_e32 v68, 0xbfb8aa3b, v153
	v_mul_f32_e32 v69, 0xbfb8aa3b, v157
	v_cvt_pk_bf16_f32 v152, v73, s0
	v_mul_f32_e32 v73, 0x3d800000, v159
	v_or_b32_e32 v61, v60, v57
	v_or_b32_sdwa v60, v66, v56 dst_sel:DWORD dst_unused:UNUSED_PAD src0_sel:DWORD src1_sel:WORD_0
	s_waitcnt vmcnt(13)
	v_lshlrev_b32_e32 v57, 16, v168
	v_lshlrev_b32_e32 v56, 16, v166
	v_pk_mul_f32 v[14:15], v[62:63], v[14:15]
	v_exp_f32_e32 v68, v68
	v_mul_f32_e32 v72, 0xbfb8aa3b, v155
	v_exp_f32_e32 v69, v69
	v_mul_f32_e32 v90, v73, v136
	v_mul_f32_e32 v73, 0xbfb8aa3b, v135
	v_cvt_pk_bf16_f32 v62, v14, v15
	v_pk_mul_f32 v[14:15], v[64:65], v[56:57]
	s_lshl_b64 s[8:9], s[56:57], 11
	v_exp_f32_e32 v72, v72
	v_exp_f32_e32 v73, v73
	v_cvt_pk_bf16_f32 v14, v14, v15
	v_lshl_add_u64 v[74:75], v[8:9], 0, s[8:9]
	v_lshl_add_u64 v[82:83], v[8:9], 0, s[0:1]
	s_lshl_b64 s[0:1], s[4:5], 11
	v_lshrrev_b32_e32 v15, 16, v14
	v_lshl_add_u32 v144, s14, 9, v119
	v_lshl_add_u32 v147, s15, 9, v120
	v_lshl_add_u32 v151, s16, 9, v121
	v_lshl_add_u32 v145, s17, 9, v122
	v_lshl_add_u64 v[86:87], v[8:9], 0, s[0:1]
	v_cvt_pk_bf16_f32 v155, v90, s0
	s_lshl_b64 s[0:1], s[42:43], 11
	s_lshl_b32 s66, s3, 10
	global_store_short v[74:75], v143, off
	global_store_short v[78:79], v146, off
	global_store_short v[84:85], v150, off
	global_store_short v[88:89], v154, off
	v_lshrrev_b32_e32 v63, 16, v62
	v_and_b32_e32 v56, 0xffff0000, v14
	v_lshlrev_b32_e32 v64, 16, v14
	ds_write_b16 v140, v62 offset:32768
	ds_write_b16 v144, v143
	ds_write_b16 v144, v14 offset:32768
	ds_write_b16 v147, v146
	ds_write_b16 v147, v63 offset:32768
	ds_write_b16 v151, v150
	ds_write_b16 v151, v15 offset:32768
	ds_write_b16 v145, v154
	s_waitcnt vmcnt(15)
	v_lshlrev_b32_e32 v15, 16, v163
	v_lshlrev_b32_e32 v14, 16, v161
	v_lshl_add_u64 v[90:91], v[8:9], 0, s[0:1]
	v_lshl_add_u64 v[158:159], v[10:11], 0, s[66:67]
	global_store_short v[82:83], v148, off
	global_store_short v[86:87], v152, off
	global_store_short v[90:91], v155, off
	global_store_dwordx4 v[158:159], v[58:61], off
	v_pk_mul_f32 v[14:15], v[68:69], v[14:15]
	v_or_b32_e32 v57, v56, v63
	s_waitcnt vmcnt(17)
	v_lshlrev_b32_e32 v59, 16, v164
	v_lshlrev_b32_e32 v58, 16, v162
	v_cvt_pk_bf16_f32 v60, v14, v15
	v_pk_mul_f32 v[14:15], v[72:73], v[58:59]
	v_or_b32_sdwa v56, v64, v62 dst_sel:DWORD dst_unused:UNUSED_PAD src0_sel:DWORD src1_sel:WORD_0
	v_cvt_pk_bf16_f32 v14, v14, v15
	v_lshrrev_b32_e32 v61, 16, v60
	v_and_b32_e32 v58, 0xffff0000, v14
	v_lshlrev_b32_e32 v62, 16, v14
	v_or_b32_e32 v59, v58, v61
	v_or_b32_sdwa v58, v62, v60 dst_sel:DWORD dst_unused:UNUSED_PAD src0_sel:DWORD src1_sel:WORD_0
	s_add_i32 s3, s3, 1
	v_lshl_add_u32 v149, s18, 9, v123
	v_lshl_add_u32 v153, s19, 9, v124
	v_lshl_add_u32 v156, s20, 9, v125
	v_lshrrev_b32_e32 v15, 16, v14
	ds_write_b16 v145, v60 offset:32768
	ds_write_b16 v149, v148
	ds_write_b16 v149, v14 offset:32768
	ds_write_b16 v153, v152
	ds_write_b16 v153, v61 offset:32768
	ds_write_b16 v156, v155
	ds_write_b16 v156, v15 offset:32768
	global_store_dwordx4 v[158:159], v[56:59], off offset:512
	s_cmp_eq_u32 s3, 4
	s_nop 0
	v_mov_b32_e32 v58, v135
	s_cbranch_scc0 .LBB0_224
	s_ashr_i32 s3, s2, 31
	s_lshl_b64 s[0:1], s[2:3], 10
	v_lshl_add_u64 v[0:1], v[22:23], 0, s[0:1]
	global_store_dword v[0:1], v136, off
	v_mov_b32_e32 v0, 0
	v_mov_b32_e32 v1, 0
	v_mov_b32_e32 v2, 0
	v_mov_b32_e32 v3, 0
	v_mov_b32_e32 v4, 0
	v_mov_b32_e32 v5, 0
	v_mov_b32_e32 v6, 0
	v_mov_b32_e32 v7, 0
	v_mov_b32_e32 v8, 0
	v_mov_b32_e32 v9, 0
	v_mov_b32_e32 v10, 0
	v_mov_b32_e32 v11, 0
	v_mov_b32_e32 v12, 0
	v_mov_b32_e32 v13, 0
	v_mov_b32_e32 v14, 0
	v_mov_b32_e32 v15, 0
	s_waitcnt lgkmcnt(0)
	s_barrier
	s_and_b32 s4, s2, 3
	s_lshl_b32 s4, s4, 22
	s_lshr_b32 s5, s2, 2
	s_lshl_b32 s5, s5, 15
	s_or_b32 s4, s4, s5
	s_add_u32 s4, s4, 0xe800000
	v_lshlrev_b32_e32 v196, 4, v16
	v_mov_b32_e32 v197, 0
	v_add_u32_e32 v196, s4, v196
	v_lshl_add_u64 v[196:197], v[184:185], 0, v[196:197]
	v_and_b32_e32 v198, 31, v16
	v_bfe_u32 v199, v16, 5, 1
	v_lshrrev_b32_e32 v200, 6, v16
	v_lshlrev_b32_e32 v201, 9, v198
	v_lshl_add_u32 v201, v199, 3, v201
	v_and_b32_e32 v202, 15, v198
	v_lshlrev_b32_e32 v200, 1, v200
	v_xor_b32_e32 v203, v200, v202
	v_lshl_add_u32 v203, v203, 4, v201
	v_xor_b32_e32 v204, 16, v203
	ds_read_b64 v[208:209], v203
	ds_read_b64 v[210:211], v204
	s_waitcnt lgkmcnt(0)
	global_store_dwordx4 v[196:197], v[208:211], off
	v_lshl_add_u64 v[196:197], v[196:197], 0, s[86:87]
	ds_read_b64 v[212:213], v203 offset:16384
	ds_read_b64 v[214:215], v204 offset:16384
	s_waitcnt lgkmcnt(0)
	global_store_dwordx4 v[196:197], v[212:215], off
	v_lshl_add_u64 v[196:197], v[196:197], 0, s[86:87]
	v_add_u32_e32 v205, 8, v200
	v_xor_b32_e32 v203, v205, v202
	v_lshl_add_u32 v203, v203, 4, v201
	v_xor_b32_e32 v204, 16, v203
	ds_read_b64 v[208:209], v203
	ds_read_b64 v[210:211], v204
	s_waitcnt lgkmcnt(0)
	global_store_dwordx4 v[196:197], v[208:211], off
	v_lshl_add_u64 v[196:197], v[196:197], 0, s[86:87]
	ds_read_b64 v[212:213], v203 offset:16384
	ds_read_b64 v[214:215], v204 offset:16384
	s_waitcnt lgkmcnt(0)
	global_store_dwordx4 v[196:197], v[212:215], off
	v_lshl_add_u64 v[196:197], v[196:197], 0, s[86:87]
	v_add_u32_e32 v205, 16, v200
	v_xor_b32_e32 v203, v205, v202
	v_lshl_add_u32 v203, v203, 4, v201
	v_xor_b32_e32 v204, 16, v203
	ds_read_b64 v[208:209], v203
	ds_read_b64 v[210:211], v204
	s_waitcnt lgkmcnt(0)
	global_store_dwordx4 v[196:197], v[208:211], off
	v_lshl_add_u64 v[196:197], v[196:197], 0, s[86:87]
	ds_read_b64 v[212:213], v203 offset:16384
	ds_read_b64 v[214:215], v204 offset:16384
	s_waitcnt lgkmcnt(0)
	global_store_dwordx4 v[196:197], v[212:215], off
	v_lshl_add_u64 v[196:197], v[196:197], 0, s[86:87]
	v_add_u32_e32 v205, 24, v200
	v_xor_b32_e32 v203, v205, v202
	v_lshl_add_u32 v203, v203, 4, v201
	v_xor_b32_e32 v204, 16, v203
	ds_read_b64 v[208:209], v203
	ds_read_b64 v[210:211], v204
	s_waitcnt lgkmcnt(0)
	global_store_dwordx4 v[196:197], v[208:211], off
	v_lshl_add_u64 v[196:197], v[196:197], 0, s[86:87]
	ds_read_b64 v[212:213], v203 offset:16384
	ds_read_b64 v[214:215], v204 offset:16384
	s_waitcnt lgkmcnt(0)
	global_store_dwordx4 v[196:197], v[212:215], off
	s_mov_b64 s[0:1], exec
	v_readlane_b32 s4, v255, 19
	v_readlane_b32 s5, v255, 20
	s_and_b64 s[4:5], s[0:1], s[4:5]
	s_mov_b64 exec, s[4:5]
	s_cbranch_execz .LBB0_222
	v_add_u32_e32 v0, v17, v95
	ds_read_b128 v[0:3], v0
	v_add_u32_e32 v4, v94, v95
	ds_read_b128 v[4:7], v4 offset:32768
	v_add_u32_e32 v56, v17, v96
	ds_read_b128 v[56:59], v56
	v_add_u32_e32 v60, v94, v96
	ds_read_b128 v[60:63], v60 offset:32768
	v_add_u32_e32 v64, v17, v97
	s_waitcnt lgkmcnt(2)
	v_mfma_f32_32x32x16_bf16 v[0:15], v[0:3], v[4:7], 0
	s_waitcnt lgkmcnt(0)
	v_mfma_f32_32x32x16_bf16 v[0:15], v[56:59], v[60:63], v[0:15]
	ds_read_b128 v[56:59], v64
	v_add_u32_e32 v60, v94, v97
	ds_read_b128 v[60:63], v60 offset:32768
	v_add_u32_e32 v64, v17, v98
	s_waitcnt lgkmcnt(0)
	v_mfma_f32_32x32x16_bf16 v[0:15], v[56:59], v[60:63], v[0:15]
	ds_read_b128 v[56:59], v64
	v_add_u32_e32 v60, v94, v98
	ds_read_b128 v[60:63], v60 offset:32768
	v_add_u32_e32 v64, v17, v99
	s_waitcnt lgkmcnt(0)
	v_mfma_f32_32x32x16_bf16 v[0:15], v[56:59], v[60:63], v[0:15]
	ds_read_b128 v[56:59], v64
	v_add_u32_e32 v60, v94, v99
	ds_read_b128 v[60:63], v60 offset:32768
	v_add_u32_e32 v64, v17, v100
	s_waitcnt lgkmcnt(0)
	v_mfma_f32_32x32x16_bf16 v[0:15], v[56:59], v[60:63], v[0:15]
	ds_read_b128 v[56:59], v64
	v_add_u32_e32 v60, v94, v100
	ds_read_b128 v[60:63], v60 offset:32768
	v_add_u32_e32 v64, v17, v101
	s_waitcnt lgkmcnt(0)
	v_mfma_f32_32x32x16_bf16 v[0:15], v[56:59], v[60:63], v[0:15]
	ds_read_b128 v[56:59], v64
	v_add_u32_e32 v60, v94, v101
	ds_read_b128 v[60:63], v60 offset:32768
	v_add_u32_e32 v64, v17, v102
	s_waitcnt lgkmcnt(0)
	v_mfma_f32_32x32x16_bf16 v[0:15], v[56:59], v[60:63], v[0:15]
	ds_read_b128 v[56:59], v64
	v_add_u32_e32 v60, v94, v102
	ds_read_b128 v[60:63], v60 offset:32768
	v_add_u32_e32 v64, v17, v103
	s_waitcnt lgkmcnt(0)
	v_mfma_f32_32x32x16_bf16 v[0:15], v[56:59], v[60:63], v[0:15]
	ds_read_b128 v[56:59], v64
	v_add_u32_e32 v60, v94, v103
	ds_read_b128 v[60:63], v60 offset:32768
	v_add_u32_e32 v64, v17, v104
	s_waitcnt lgkmcnt(0)
	v_mfma_f32_32x32x16_bf16 v[0:15], v[56:59], v[60:63], v[0:15]
	ds_read_b128 v[56:59], v64
	v_add_u32_e32 v60, v94, v104
	ds_read_b128 v[60:63], v60 offset:32768
	v_add_u32_e32 v64, v17, v105
	s_waitcnt lgkmcnt(0)
	v_mfma_f32_32x32x16_bf16 v[0:15], v[56:59], v[60:63], v[0:15]
	ds_read_b128 v[56:59], v64
	v_add_u32_e32 v60, v94, v105
	ds_read_b128 v[60:63], v60 offset:32768
	v_add_u32_e32 v64, v17, v106
	s_waitcnt lgkmcnt(0)
	v_mfma_f32_32x32x16_bf16 v[0:15], v[56:59], v[60:63], v[0:15]
	ds_read_b128 v[56:59], v64
	v_add_u32_e32 v60, v94, v106
	ds_read_b128 v[60:63], v60 offset:32768
	v_add_u32_e32 v64, v17, v107
	s_waitcnt lgkmcnt(0)
	v_mfma_f32_32x32x16_bf16 v[0:15], v[56:59], v[60:63], v[0:15]
	ds_read_b128 v[56:59], v64
	v_add_u32_e32 v60, v94, v107
	ds_read_b128 v[60:63], v60 offset:32768
	v_add_u32_e32 v64, v17, v108
	s_waitcnt lgkmcnt(0)
	v_mfma_f32_32x32x16_bf16 v[0:15], v[56:59], v[60:63], v[0:15]
	ds_read_b128 v[56:59], v64
	v_add_u32_e32 v60, v94, v108
	ds_read_b128 v[60:63], v60 offset:32768
	v_add_u32_e32 v64, v17, v109
	s_waitcnt lgkmcnt(0)
	v_mfma_f32_32x32x16_bf16 v[0:15], v[56:59], v[60:63], v[0:15]
	ds_read_b128 v[56:59], v64
	v_add_u32_e32 v60, v94, v109
	ds_read_b128 v[60:63], v60 offset:32768
	v_add_u32_e32 v64, v17, v110
	s_waitcnt lgkmcnt(0)
	v_mfma_f32_32x32x16_bf16 v[0:15], v[56:59], v[60:63], v[0:15]
	ds_read_b128 v[56:59], v64
	v_add_u32_e32 v60, v94, v110
	ds_read_b128 v[60:63], v60 offset:32768
	s_waitcnt lgkmcnt(0)
	v_mfma_f32_32x32x16_bf16 v[0:15], v[56:59], v[60:63], v[0:15]
	s_branch .LBB0_222
